# stack on the MFMA-trim version: merged waits, invariant LDS base, DMA wait-state fillers, 6-DMA segment heads run at the previous load tail, tile scheduler uses shift/mask for the constant group size
# speedup vs baseline: 1.0042x; 1.0042x over previous
;     DI bool next(int i, Unit& u) const {
;         const long L = (long)i * G + c; const int nMz = nM * nZ, nwg = nMz * nN; if (L >= nwg) return false;
;         int wgid = (int)L; { const int q = nwg / NXCD, r = nwg % NXCD, xcd = wgid % NXCD, off = wgid / NXCD; wgid = (xcd < r ? xcd * (q + 1) : r * (q + 1) + (xcd - r) * q) + off; }
;         const int nig = WGM * nN, gid = wgid / nig, fm = gid * WGM, gsz = (nMz - fm) < WGM ? (nMz - fm) : WGM;
;         const int pmz = fm + ((wgid % nig) % gsz); u.pn = (wgid % nig) / gsz;
;         const int z = pmz / nM, pm = pmz - z * nM; u.pm = pm; u.z = z;
;         if (bmode == 0) u.b = B + (unsigned)z * sBz + (unsigned)u.pn * 256u * (unsigned)ldb2;
;         else if (bmode == 1) u.b = B + (unsigned)z * sBz + (unsigned)((u.pn >> 4) * 4096 + 4 * (u.pn & 15)) * (unsigned)ldb2;
;         else u.b = B + (unsigned)z * sBz + (unsigned)u.pn * 4u * 16384u;
;         if (mode == 0) { const unsigned a = A + (unsigned)z * sAz + (unsigned)pm * 256u * (unsigned)lda2; u.a0 = a; u.a1 = a + 64u * lda2; u.a2 = a + 128u * lda2; u.a3 = a + 192u * lda2; }
;         else if (mode == 1) { const int g = pm * 256; u.a0 = A + (unsigned)hpad_row(g) * lda2; u.a1 = A + (unsigned)hpad_row(g + 64) * lda2; u.a2 = A + (unsigned)hpad_row(g + 128) * lda2; u.a3 = A + (unsigned)hpad_row(g + 192) * lda2; }
.LBB0_90:
	v_readlane_b32 s0, v255, 1
	s_add_i32 s95, s0, 1
	s_mul_i32 s19, s95, s3
	s_mul_hi_i32 s18, s95, s3
	s_add_u32 s44, s19, s2
	s_addc_u32 s45, s18, s77
	v_mov_b64_e32 v[128:129], s[48:49]
	v_cmp_ge_i64_e64 s[18:19], s[44:45], v[128:129]
	v_cmp_lt_i64_e64 s[20:21], s[44:45], v[128:129]
	s_and_b64 vcc, exec, s[18:19]
	s_mov_b32 s45, s58
	s_mov_b32 s54, s41
	s_mov_b32 s55, s27
	s_mov_b32 s56, s61
	s_mov_b32 s57, s60
	s_cbranch_vccnz .LBB0_109
	s_ashr_i32 s1, s44, 31
	s_lshr_b32 s1, s1, 29
	s_add_i32 s1, s44, s1
	s_ashr_i32 s40, s1, 3
	s_and_b32 s1, s1, -8
	s_sub_i32 s1, s44, s1
	s_lshr_b32 s44, s1, 31
	v_readlane_b32 s0, v254, 51
	s_or_b32 s44, s0, s44
	s_mul_i32 s1, s1, s44
	s_add_i32 s1, s1, s40
	s_mul_hi_i32 s40, s1, 0x2e8ba2e9
	s_lshr_b32 s44, s40, 31
	s_ashr_i32 s40, s40, 6
	s_add_i32 s40, s40, s44
	s_lshl_b32 s44, s40, 3
	s_sub_i32 s45, s35, s44
	s_min_i32 s45, s45, 8
	s_mulk_i32 s40, 0x160
	s_sub_i32 s1, s1, s40
	v_readlane_b32 s0, v255, 6
	s_lshr_b32 s59, s1, 3
	s_and_b32 s1, s1, 7
	s_add_i32 s44, s44, s1
	s_abs_i32 s40, s44
	s_ashr_i32 s1, s44, 31
	s_mul_hi_u32 s44, s40, s0
	s_mul_i32 s44, s44, s35
	s_sub_i32 s40, s40, s44
	s_sub_i32 s44, s40, s35
	s_cmp_ge_u32 s40, s35
	s_cselect_b32 s40, s44, s40
	s_sub_i32 s44, s40, s35
	s_cmp_ge_u32 s40, s35
	s_cselect_b32 s40, s44, s40
	s_xor_b32 s40, s40, s1
	s_sub_i32 s89, s40, s1
	s_lshl_b32 s54, s89, 8
	s_cmpk_gt_i32 s89, 0x7f
	s_mov_b64 s[44:45], -1
	s_cbranch_scc0 .LBB0_93
	s_add_i32 s1, s54, 0xffff8000
	s_lshr_b32 s1, s1, 8
	s_mul_i32 s55, s1, 0x102
	s_mov_b64 s[44:45], 0

; #define G_STAGE_A(bufoff, p0, p1, koff) do { \
;         __builtin_amdgcn_global_load_lds((const unsigned*)(gbase + (size_t)(unsigned)((p0) + (koff) + voffA[0])), (LAS unsigned*)(lds + (bufoff) + ldsw), 16, 0, 0); \
;         __builtin_amdgcn_global_load_lds((const unsigned*)(gbase + (size_t)(unsigned)((p1) + (koff) + voffA[1])), (LAS unsigned*)(lds + (bufoff) + ldsw + 8192), 16, 0, 0); } while (0)
; #define G_STAGE_B(bufoff, p, koff) do { \
;         __builtin_amdgcn_global_load_lds((const unsigned*)(gbase + (size_t)(unsigned)((p) + (koff) + voffB[0])), (LAS unsigned*)(lds + (bufoff) + ldsw), 16, 0, 0); \
;         __builtin_amdgcn_global_load_lds((const unsigned*)(gbase + (size_t)(unsigned)((p) + (koff) + voffB[1])), (LAS unsigned*)(lds + (bufoff) + ldsw + 8192), 16, 0, 0); } while (0)
; #define G_LDA(dst, b, h) do { _Pragma("unroll") for (int m = 0; m < 4; ++m) _Pragma("unroll") for (int k = 0; k < 2; ++k) dst[m][k] = *(const LAS bf16x8*)(lds + G_SA(b, h) + aoff + m * 2048 + k * 1024); } while (0)
; #define G_LDB(dst, b, h) do { _Pragma("unroll") for (int n = 0; n < 2; ++n) _Pragma("unroll") for (int k = 0; k < 2; ++k) dst[n][k] = *(const LAS bf16x8*)(lds + G_SB(b, h) + boff + n * 2048 + k * 1024); } while (0)
; #define G_WAIT_V(n) asm volatile("s_waitcnt vmcnt(" #n ")" ::: "memory")
; #define G_WAIT_L(n) asm volatile("s_waitcnt lgkmcnt(" #n ")" ::: "memory")
; template <class Epi>
; DI void gemm_phase(LAS unsigned char* lds, const Sched& S, const Epi& E, const int K) {
;     ...
;             const unsigned k1 = (unsigned)(t + 1) * kstepA;
;             const unsigned k2 = last ? 0u : (unsigned)(t + 2) * kstepA, k3 = k2 + kstepA;
;             const unsigned kb2 = last ? 0u : (unsigned)(t + 2) * kstepB, kb3 = kb2 + kstepB;
;             const unsigned x0 = last ? n0 : cur.a0, x1 = last ? n1 : cur.a1, x2 = last ? n2 : cur.a2, x3 = last ? n3 : cur.a3;
;             const unsigned xb = last ? nB : cur.b;
;     ...
;             G_LDB(B0, 0, 0); G_LDB(B1, 0, 1); G_SCHED; G_LDA(At, 0, 0); G_STAGE_A(G_SA(1, 1), cur.a2, cur.a3, k1);
;             G_WAIT_V(8); G_WAIT_L(0); G_BAR; G_MMA(0, 0, At, B0); G_MMA(0, 1, At, B1); G_BAR; G_SCHED;
;             G_LDA(At, 0, 1); G_STAGE_B(G_SB(0, 0), xb, kb2); G_STAGE_B(G_SB(0, 1), xb + hstepB, kb2); G_STAGE_A(G_SA(0, 0), x0, x1, k2);
;             G_WAIT_V(8); G_WAIT_L(0); G_BAR; G_MMA(1, 0, At, B0); G_MMA(1, 1, At, B1); G_BAR; G_SCHED;
.LBB0_110:
	s_add_i32 s91, s90, 0x100
	s_cmp_eq_u32 s44, 28
	s_cselect_b32 s40, 0, s91
	s_cselect_b32 s46, s54, s41
	s_cselect_b32 s47, s56, s61
	s_cselect_b32 s88, s55, s27
	s_cselect_b32 s62, s45, s58
	s_cselect_b32 vcc_hi, s57, s60
	s_add_i32 s63, 0, 0x10000
	s_add_i32 s0, 0, 0x14000
	ds_read_b128 v[130:133], v252
	ds_read_b128 v[134:137], v252 offset:1024
	ds_read_b128 v[138:141], v252 offset:2048
	ds_read_b128 v[142:145], v252 offset:3072
	ds_read_b128 v[146:149], v252 offset:16384
	ds_read_b128 v[150:153], v252 offset:17408
	ds_read_b128 v[154:157], v252 offset:18432
	ds_read_b128 v[162:165], v252 offset:19456
	v_add_u32_e32 v158, s90, v129
	s_add_i32 m0, s78, 0xc000
	v_add_u32_e32 v183, s90, v128
	ds_read_b128 v[166:169], v214
	ds_read_b128 v[170:173], v214 offset:1024
	ds_read_b128 v[174:177], v214 offset:2048
	ds_read_b128 v[178:181], v214 offset:3072
	ds_read_b128 v[194:197], v214 offset:4096
	ds_read_b128 v[198:201], v214 offset:5120
	ds_read_b128 v[216:219], v214 offset:6144
	ds_read_b128 v[220:223], v214 offset:7168
	global_load_lds_dwordx4 v158, s[82:83]
	s_add_i32 m0, s78, 0xe000
	s_or_b32 vcc_lo, s40, 0x80
	global_load_lds_dwordx4 v183, s[82:83]
	s_add_i32 s90, s40, vcc_hi
	s_add_i32 s63, s63, s50
	v_add_u32_e32 v158, s90, v204
	s_mov_b32 m0, s63
	s_waitcnt vmcnt(8) lgkmcnt(0)
	s_barrier
	s_setprio 1
	v_mfma_f32_16x16x32_bf16 v[124:127], v[130:133], v[166:169], v[124:127]
	v_mfma_f32_16x16x32_bf16 v[120:123], v[138:141], v[166:169], v[120:123]
	v_mfma_f32_16x16x32_bf16 v[116:119], v[130:133], v[174:177], v[116:119]
	v_mfma_f32_16x16x32_bf16 v[112:115], v[138:141], v[174:177], v[112:115]
	v_mfma_f32_16x16x32_bf16 v[108:111], v[130:133], v[194:197], v[108:111]
	v_mfma_f32_16x16x32_bf16 v[104:107], v[138:141], v[194:197], v[104:107]
	v_mfma_f32_16x16x32_bf16 v[100:103], v[130:133], v[216:219], v[100:103]
	v_mfma_f32_16x16x32_bf16 v[96:99], v[138:141], v[216:219], v[96:99]
	v_mfma_f32_16x16x32_bf16 v[124:127], v[134:137], v[170:173], v[124:127]
	v_mfma_f32_16x16x32_bf16 v[120:123], v[142:145], v[170:173], v[120:123]
	v_mfma_f32_16x16x32_bf16 v[116:119], v[134:137], v[178:181], v[116:119]
	v_mfma_f32_16x16x32_bf16 v[112:115], v[142:145], v[178:181], v[112:115]
	v_mfma_f32_16x16x32_bf16 v[108:111], v[134:137], v[198:201], v[108:111]
	v_mfma_f32_16x16x32_bf16 v[104:107], v[142:145], v[198:201], v[104:107]
	v_mfma_f32_16x16x32_bf16 v[100:103], v[134:137], v[220:223], v[100:103]
	v_mfma_f32_16x16x32_bf16 v[96:99], v[142:145], v[220:223], v[96:99]
	v_mfma_f32_16x16x32_bf16 v[92:95], v[146:149], v[166:169], v[92:95]
	v_mfma_f32_16x16x32_bf16 v[88:91], v[154:157], v[166:169], v[88:91]
	v_mfma_f32_16x16x32_bf16 v[84:87], v[146:149], v[174:177], v[84:87]
	v_mfma_f32_16x16x32_bf16 v[80:83], v[154:157], v[174:177], v[80:83]
	v_mfma_f32_16x16x32_bf16 v[76:79], v[146:149], v[194:197], v[76:79]
	v_mfma_f32_16x16x32_bf16 v[72:75], v[154:157], v[194:197], v[72:75]
	v_mfma_f32_16x16x32_bf16 v[68:71], v[146:149], v[216:219], v[68:71]
	v_mfma_f32_16x16x32_bf16 v[64:67], v[154:157], v[216:219], v[64:67]
	v_mfma_f32_16x16x32_bf16 v[92:95], v[150:153], v[170:173], v[92:95]
	v_mfma_f32_16x16x32_bf16 v[88:91], v[162:165], v[170:173], v[88:91]
	v_mfma_f32_16x16x32_bf16 v[84:87], v[150:153], v[178:181], v[84:87]
	v_mfma_f32_16x16x32_bf16 v[80:83], v[162:165], v[178:181], v[80:83]
	v_mfma_f32_16x16x32_bf16 v[76:79], v[150:153], v[198:201], v[76:79]
	v_mfma_f32_16x16x32_bf16 v[72:75], v[162:165], v[198:201], v[72:75]
	v_mfma_f32_16x16x32_bf16 v[68:71], v[150:153], v[220:223], v[68:71]
	v_mfma_f32_16x16x32_bf16 v[64:67], v[162:165], v[220:223], v[64:67]
	s_setprio 0
	s_barrier
	ds_read_b128 v[166:169], v214 offset:16384
	ds_read_b128 v[170:173], v214 offset:17408
	ds_read_b128 v[174:177], v214 offset:18432
	ds_read_b128 v[178:181], v214 offset:19456
	ds_read_b128 v[194:197], v214 offset:20480
	ds_read_b128 v[198:201], v214 offset:21504
	ds_read_b128 v[216:219], v214 offset:22528
	ds_read_b128 v[220:223], v214 offset:23552
	global_load_lds_dwordx4 v158, s[82:83]
	s_add_i32 m0, s63, 0x2000
	s_add_i32 s63, vcc_hi, 0x80000
	v_add_u32_e32 v158, s90, v206
	s_add_i32 s90, s63, s40
	s_add_i32 s0, s0, s50
	v_add_u32_e32 v183, s90, v204
	global_load_lds_dwordx4 v158, s[82:83]
	s_mov_b32 m0, s0
	v_add_u32_e32 v158, s90, v206
	global_load_lds_dwordx4 v183, s[82:83]
	s_add_i32 m0, s0, 0x2000
	v_add_u32_e32 v159, s46, v205
	global_load_lds_dwordx4 v158, s[82:83]
	v_add_u32_e32 v158, s62, v161
	v_add_u32_e32 v182, s40, v158
	s_mov_b32 m0, s78
	v_add_u32_e32 v183, s40, v159
	global_load_lds_dwordx4 v182, s[82:83]
	s_mov_b32 m0, s79
	s_nop 0
	global_load_lds_dwordx4 v183, s[82:83]
	s_waitcnt vmcnt(8) lgkmcnt(0)
	s_barrier
; #define G_STAGE_A(bufoff, p0, p1, koff) do { \
;         __builtin_amdgcn_global_load_lds((const unsigned*)(gbase + (size_t)(unsigned)((p0) + (koff) + voffA[0])), (LAS unsigned*)(lds + (bufoff) + ldsw), 16, 0, 0); \
;         __builtin_amdgcn_global_load_lds((const unsigned*)(gbase + (size_t)(unsigned)((p1) + (koff) + voffA[1])), (LAS unsigned*)(lds + (bufoff) + ldsw + 8192), 16, 0, 0); } while (0)
; #define G_LDA(dst, b, h) do { _Pragma("unroll") for (int m = 0; m < 4; ++m) _Pragma("unroll") for (int k = 0; k < 2; ++k) dst[m][k] = *(const LAS bf16x8*)(lds + G_SA(b, h) + aoff + m * 2048 + k * 1024); } while (0)
; #define G_LDB(dst, b, h) do { _Pragma("unroll") for (int n = 0; n < 2; ++n) _Pragma("unroll") for (int k = 0; k < 2; ++k) dst[n][k] = *(const LAS bf16x8*)(lds + G_SB(b, h) + boff + n * 2048 + k * 1024); } while (0)
; #define G_MMA(ai, bj, At, Bt) do { __builtin_amdgcn_s_setprio(1); _Pragma("unroll") for (int m = 0; m < 4; ++m) _Pragma("unroll") for (int n = 0; n < 2; ++n) _Pragma("unroll") for (int k = 0; k < 2; ++k) \
;         acc[ai][bj][m][n] = __builtin_amdgcn_mfma_f32_16x16x32_bf16(Bt[n][k], At[m][k], acc[ai][bj][m][n], 0, 0, 0); __builtin_amdgcn_s_setprio(0); } while (0)
; #define G_WAIT_V(n) asm volatile("s_waitcnt vmcnt(" #n ")" ::: "memory")
; #define G_WAIT_L(n) asm volatile("s_waitcnt lgkmcnt(" #n ")" ::: "memory")
; #define G_BAR __builtin_amdgcn_s_barrier()
; #define G_SCHED __builtin_amdgcn_sched_barrier(0)
; template <class Epi>
; DI void gemm_phase(LAS unsigned char* lds, const Sched& S, const Epi& E, const int K) {
;     ...
;             G_WAIT_V(8); G_WAIT_L(0); G_BAR; G_MMA(1, 0, At, B0); G_MMA(1, 1, At, B1); G_BAR; G_SCHED;
;             G_LDB(B0, 1, 0); G_LDB(B1, 1, 1); G_SCHED; G_LDA(At, 1, 0); G_STAGE_A(G_SA(0, 1), x2, x3, k2);
;             G_WAIT_V(8); G_WAIT_L(0); G_BAR; G_MMA(0, 0, At, B0); G_MMA(0, 1, At, B1); G_BAR; G_SCHED;
	s_setprio 1
	v_mfma_f32_16x16x32_bf16 v[60:63], v[130:133], v[166:169], v[60:63]
	v_mfma_f32_16x16x32_bf16 v[56:59], v[138:141], v[166:169], v[56:59]
	v_mfma_f32_16x16x32_bf16 v[52:55], v[130:133], v[174:177], v[52:55]
	v_mfma_f32_16x16x32_bf16 v[48:51], v[138:141], v[174:177], v[48:51]
	v_mfma_f32_16x16x32_bf16 v[44:47], v[130:133], v[194:197], v[44:47]
	v_mfma_f32_16x16x32_bf16 v[40:43], v[138:141], v[194:197], v[40:43]
	v_mfma_f32_16x16x32_bf16 v[36:39], v[130:133], v[216:219], v[36:39]
	v_mfma_f32_16x16x32_bf16 v[32:35], v[138:141], v[216:219], v[32:35]
	v_mfma_f32_16x16x32_bf16 v[60:63], v[134:137], v[170:173], v[60:63]
	v_mfma_f32_16x16x32_bf16 v[56:59], v[142:145], v[170:173], v[56:59]
	v_mfma_f32_16x16x32_bf16 v[52:55], v[134:137], v[178:181], v[52:55]
	v_mfma_f32_16x16x32_bf16 v[48:51], v[142:145], v[178:181], v[48:51]
	v_mfma_f32_16x16x32_bf16 v[44:47], v[134:137], v[198:201], v[44:47]
	v_mfma_f32_16x16x32_bf16 v[40:43], v[142:145], v[198:201], v[40:43]
	v_mfma_f32_16x16x32_bf16 v[36:39], v[134:137], v[220:223], v[36:39]
	v_mfma_f32_16x16x32_bf16 v[32:35], v[142:145], v[220:223], v[32:35]
	v_mfma_f32_16x16x32_bf16 v[28:31], v[146:149], v[166:169], v[28:31]
	v_mfma_f32_16x16x32_bf16 v[24:27], v[154:157], v[166:169], v[24:27]
	v_mfma_f32_16x16x32_bf16 v[20:23], v[146:149], v[174:177], v[20:23]
	v_mfma_f32_16x16x32_bf16 v[16:19], v[154:157], v[174:177], v[16:19]
	v_mfma_f32_16x16x32_bf16 v[12:15], v[146:149], v[194:197], v[12:15]
	v_mfma_f32_16x16x32_bf16 v[8:11], v[154:157], v[194:197], v[8:11]
	v_mfma_f32_16x16x32_bf16 v[4:7], v[146:149], v[216:219], v[4:7]
	v_mfma_f32_16x16x32_bf16 v[0:3], v[154:157], v[216:219], v[0:3]
	v_mfma_f32_16x16x32_bf16 v[28:31], v[150:153], v[170:173], v[28:31]
	v_mfma_f32_16x16x32_bf16 v[24:27], v[162:165], v[170:173], v[24:27]
	v_mfma_f32_16x16x32_bf16 v[20:23], v[150:153], v[178:181], v[20:23]
	v_mfma_f32_16x16x32_bf16 v[16:19], v[162:165], v[178:181], v[16:19]
	v_mfma_f32_16x16x32_bf16 v[12:15], v[150:153], v[198:201], v[12:15]
	v_mfma_f32_16x16x32_bf16 v[8:11], v[162:165], v[198:201], v[8:11]
	v_mfma_f32_16x16x32_bf16 v[4:7], v[150:153], v[220:223], v[4:7]
	v_mfma_f32_16x16x32_bf16 v[0:3], v[162:165], v[220:223], v[0:3]
	s_setprio 0
	s_barrier
	s_add_i32 s0, 0, 0x18000
	ds_read_b128 v[130:133], v252 offset:32768
	ds_read_b128 v[134:137], v252 offset:33792
	ds_read_b128 v[138:141], v252 offset:34816
	ds_read_b128 v[142:145], v252 offset:35840
	ds_read_b128 v[146:149], v252 offset:49152
	ds_read_b128 v[150:153], v252 offset:50176
	ds_read_b128 v[154:157], v252 offset:51200
	ds_read_b128 v[162:165], v252 offset:52224
	s_add_i32 s88, s88, s40
	s_mov_b32 m0, s92
	v_add_u32_e32 v182, s88, v161
	s_add_i32 s47, s47, s40
	v_add_u32_e32 v183, s47, v205
	ds_read_b128 v[166:169], v214 offset:32768
	ds_read_b128 v[170:173], v214 offset:33792
	ds_read_b128 v[174:177], v214 offset:34816
	ds_read_b128 v[178:181], v214 offset:35840
	ds_read_b128 v[194:197], v214 offset:36864
	ds_read_b128 v[198:201], v214 offset:37888
	ds_read_b128 v[216:219], v214 offset:38912
	ds_read_b128 v[220:223], v214 offset:39936
	global_load_lds_dwordx4 v182, s[82:83]
	s_mov_b32 m0, s93
	s_add_i32 s46, 0, 0x1c000
	global_load_lds_dwordx4 v183, s[82:83]
	s_add_i32 s40, vcc_lo, vcc_hi
	s_add_i32 s0, s0, s50
	v_add_u32_e32 v182, s40, v204
	s_mov_b32 m0, s0
	s_waitcnt vmcnt(8) lgkmcnt(0)
	s_barrier
	s_setprio 1
	v_mfma_f32_16x16x32_bf16 v[124:127], v[130:133], v[166:169], v[124:127]
	v_mfma_f32_16x16x32_bf16 v[120:123], v[138:141], v[166:169], v[120:123]
	v_mfma_f32_16x16x32_bf16 v[116:119], v[130:133], v[174:177], v[116:119]
	v_mfma_f32_16x16x32_bf16 v[112:115], v[138:141], v[174:177], v[112:115]
	v_mfma_f32_16x16x32_bf16 v[108:111], v[130:133], v[194:197], v[108:111]
	v_mfma_f32_16x16x32_bf16 v[104:107], v[138:141], v[194:197], v[104:107]
	v_mfma_f32_16x16x32_bf16 v[100:103], v[130:133], v[216:219], v[100:103]
	v_mfma_f32_16x16x32_bf16 v[96:99], v[138:141], v[216:219], v[96:99]
	v_mfma_f32_16x16x32_bf16 v[124:127], v[134:137], v[170:173], v[124:127]
	v_mfma_f32_16x16x32_bf16 v[120:123], v[142:145], v[170:173], v[120:123]
	v_mfma_f32_16x16x32_bf16 v[116:119], v[134:137], v[178:181], v[116:119]
	v_mfma_f32_16x16x32_bf16 v[112:115], v[142:145], v[178:181], v[112:115]
	v_mfma_f32_16x16x32_bf16 v[108:111], v[134:137], v[198:201], v[108:111]
	v_mfma_f32_16x16x32_bf16 v[104:107], v[142:145], v[198:201], v[104:107]
	v_mfma_f32_16x16x32_bf16 v[100:103], v[134:137], v[220:223], v[100:103]
	v_mfma_f32_16x16x32_bf16 v[96:99], v[142:145], v[220:223], v[96:99]
	v_mfma_f32_16x16x32_bf16 v[92:95], v[146:149], v[166:169], v[92:95]
	v_mfma_f32_16x16x32_bf16 v[88:91], v[154:157], v[166:169], v[88:91]
	v_mfma_f32_16x16x32_bf16 v[84:87], v[146:149], v[174:177], v[84:87]
	v_mfma_f32_16x16x32_bf16 v[80:83], v[154:157], v[174:177], v[80:83]
	v_mfma_f32_16x16x32_bf16 v[76:79], v[146:149], v[194:197], v[76:79]
	v_mfma_f32_16x16x32_bf16 v[72:75], v[154:157], v[194:197], v[72:75]
	v_mfma_f32_16x16x32_bf16 v[68:71], v[146:149], v[216:219], v[68:71]
	v_mfma_f32_16x16x32_bf16 v[64:67], v[154:157], v[216:219], v[64:67]
	v_mfma_f32_16x16x32_bf16 v[92:95], v[150:153], v[170:173], v[92:95]
	v_mfma_f32_16x16x32_bf16 v[88:91], v[162:165], v[170:173], v[88:91]
	v_mfma_f32_16x16x32_bf16 v[84:87], v[150:153], v[178:181], v[84:87]
	v_mfma_f32_16x16x32_bf16 v[80:83], v[162:165], v[178:181], v[80:83]
	v_mfma_f32_16x16x32_bf16 v[76:79], v[150:153], v[198:201], v[76:79]
	v_mfma_f32_16x16x32_bf16 v[72:75], v[162:165], v[198:201], v[72:75]
	v_mfma_f32_16x16x32_bf16 v[68:71], v[150:153], v[220:223], v[68:71]
	v_mfma_f32_16x16x32_bf16 v[64:67], v[162:165], v[220:223], v[64:67]
	s_setprio 0
	s_barrier
; #define G_STAGE_A(bufoff, p0, p1, koff) do { \
;         __builtin_amdgcn_global_load_lds((const unsigned*)(gbase + (size_t)(unsigned)((p0) + (koff) + voffA[0])), (LAS unsigned*)(lds + (bufoff) + ldsw), 16, 0, 0); \
;         __builtin_amdgcn_global_load_lds((const unsigned*)(gbase + (size_t)(unsigned)((p1) + (koff) + voffA[1])), (LAS unsigned*)(lds + (bufoff) + ldsw + 8192), 16, 0, 0); } while (0)
; #define G_STAGE_B(bufoff, p, koff) do { \
;         __builtin_amdgcn_global_load_lds((const unsigned*)(gbase + (size_t)(unsigned)((p) + (koff) + voffB[0])), (LAS unsigned*)(lds + (bufoff) + ldsw), 16, 0, 0); \
;         __builtin_amdgcn_global_load_lds((const unsigned*)(gbase + (size_t)(unsigned)((p) + (koff) + voffB[1])), (LAS unsigned*)(lds + (bufoff) + ldsw + 8192), 16, 0, 0); } while (0)
; #define G_LDA(dst, b, h) do { _Pragma("unroll") for (int m = 0; m < 4; ++m) _Pragma("unroll") for (int k = 0; k < 2; ++k) dst[m][k] = *(const LAS bf16x8*)(lds + G_SA(b, h) + aoff + m * 2048 + k * 1024); } while (0)
; #define G_MMA(ai, bj, At, Bt) do { __builtin_amdgcn_s_setprio(1); _Pragma("unroll") for (int m = 0; m < 4; ++m) _Pragma("unroll") for (int n = 0; n < 2; ++n) _Pragma("unroll") for (int k = 0; k < 2; ++k) \
;         acc[ai][bj][m][n] = __builtin_amdgcn_mfma_f32_16x16x32_bf16(Bt[n][k], At[m][k], acc[ai][bj][m][n], 0, 0, 0); __builtin_amdgcn_s_setprio(0); } while (0)
; #define G_WAIT_V(n) asm volatile("s_waitcnt vmcnt(" #n ")" ::: "memory")
; #define G_WAIT_L(n) asm volatile("s_waitcnt lgkmcnt(" #n ")" ::: "memory")
; #define G_BAR __builtin_amdgcn_s_barrier()
; #define G_SCHED __builtin_amdgcn_sched_barrier(0)
; template <class Epi>
; DI void gemm_phase(LAS unsigned char* lds, const Sched& S, const Epi& E, const int K) {
;     ...
;             G_LDA(At, 1, 1); G_STAGE_B(G_SB(1, 0), xb, kb3); G_STAGE_B(G_SB(1, 1), xb + hstepB, kb3); G_STAGE_A(G_SA(1, 0), x0, x1, k3);
;             G_WAIT_V(8); G_WAIT_L(0); G_BAR; G_MMA(1, 0, At, B0); G_MMA(1, 1, At, B1); G_BAR; G_SCHED;
	ds_read_b128 v[166:169], v214 offset:49152
	ds_read_b128 v[170:173], v214 offset:50176
	ds_read_b128 v[174:177], v214 offset:51200
	ds_read_b128 v[178:181], v214 offset:52224
	ds_read_b128 v[194:197], v214 offset:53248
	ds_read_b128 v[198:201], v214 offset:54272
	ds_read_b128 v[216:219], v214 offset:55296
	ds_read_b128 v[220:223], v214 offset:56320
	global_load_lds_dwordx4 v182, s[82:83]
	v_add_u32_e32 v182, s40, v206
	s_add_i32 m0, s0, 0x2000
	s_add_i32 s0, vcc_lo, s63
	s_add_i32 s40, s46, s50
	global_load_lds_dwordx4 v182, s[82:83]
	v_add_u32_e32 v182, s0, v204
	s_mov_b32 m0, s40
	v_add_u32_e32 v158, vcc_lo, v158
	global_load_lds_dwordx4 v182, s[82:83]
	v_add_u32_e32 v182, s0, v206
	s_add_i32 m0, s40, 0x2000
	v_add_u32_e32 v183, vcc_lo, v159
	global_load_lds_dwordx4 v182, s[82:83]
	s_mov_b32 m0, s39
	s_add_i32 s44, s44, 2
	global_load_lds_dwordx4 v158, s[82:83]
	s_mov_b32 m0, s38
	s_mov_b32 s90, s91
	global_load_lds_dwordx4 v183, s[82:83]
	s_waitcnt vmcnt(8) lgkmcnt(0)
	s_barrier
	s_setprio 1
	v_mfma_f32_16x16x32_bf16 v[60:63], v[130:133], v[166:169], v[60:63]
	v_mfma_f32_16x16x32_bf16 v[56:59], v[138:141], v[166:169], v[56:59]
	v_mfma_f32_16x16x32_bf16 v[52:55], v[130:133], v[174:177], v[52:55]
	v_mfma_f32_16x16x32_bf16 v[48:51], v[138:141], v[174:177], v[48:51]
	v_mfma_f32_16x16x32_bf16 v[44:47], v[130:133], v[194:197], v[44:47]
	v_mfma_f32_16x16x32_bf16 v[40:43], v[138:141], v[194:197], v[40:43]
	v_mfma_f32_16x16x32_bf16 v[36:39], v[130:133], v[216:219], v[36:39]
	v_mfma_f32_16x16x32_bf16 v[32:35], v[138:141], v[216:219], v[32:35]
	v_mfma_f32_16x16x32_bf16 v[60:63], v[134:137], v[170:173], v[60:63]
	v_mfma_f32_16x16x32_bf16 v[56:59], v[142:145], v[170:173], v[56:59]
	v_mfma_f32_16x16x32_bf16 v[52:55], v[134:137], v[178:181], v[52:55]
	v_mfma_f32_16x16x32_bf16 v[48:51], v[142:145], v[178:181], v[48:51]
	v_mfma_f32_16x16x32_bf16 v[44:47], v[134:137], v[198:201], v[44:47]
	v_mfma_f32_16x16x32_bf16 v[40:43], v[142:145], v[198:201], v[40:43]
	v_mfma_f32_16x16x32_bf16 v[36:39], v[134:137], v[220:223], v[36:39]
	v_mfma_f32_16x16x32_bf16 v[32:35], v[142:145], v[220:223], v[32:35]
	v_mfma_f32_16x16x32_bf16 v[28:31], v[146:149], v[166:169], v[28:31]
	v_mfma_f32_16x16x32_bf16 v[24:27], v[154:157], v[166:169], v[24:27]
	v_mfma_f32_16x16x32_bf16 v[20:23], v[146:149], v[174:177], v[20:23]
	v_mfma_f32_16x16x32_bf16 v[16:19], v[154:157], v[174:177], v[16:19]
	v_mfma_f32_16x16x32_bf16 v[12:15], v[146:149], v[194:197], v[12:15]
	v_mfma_f32_16x16x32_bf16 v[8:11], v[154:157], v[194:197], v[8:11]
	v_mfma_f32_16x16x32_bf16 v[4:7], v[146:149], v[216:219], v[4:7]
	v_mfma_f32_16x16x32_bf16 v[0:3], v[154:157], v[216:219], v[0:3]
	v_mfma_f32_16x16x32_bf16 v[28:31], v[150:153], v[170:173], v[28:31]
	v_mfma_f32_16x16x32_bf16 v[24:27], v[162:165], v[170:173], v[24:27]
	v_mfma_f32_16x16x32_bf16 v[20:23], v[150:153], v[178:181], v[20:23]
	v_mfma_f32_16x16x32_bf16 v[16:19], v[162:165], v[178:181], v[16:19]
	v_mfma_f32_16x16x32_bf16 v[12:15], v[150:153], v[198:201], v[12:15]
	v_mfma_f32_16x16x32_bf16 v[8:11], v[162:165], v[198:201], v[8:11]
	v_mfma_f32_16x16x32_bf16 v[4:7], v[150:153], v[220:223], v[4:7]
	v_mfma_f32_16x16x32_bf16 v[0:3], v[162:165], v[220:223], v[0:3]
	s_setprio 0
	s_barrier
	s_cmp_gt_u32 s44, 29
	s_cbranch_scc0 .LBB0_110
	v_readlane_b32 s44, v254, 63
	v_readlane_b32 s45, v255, 0
	s_and_b64 vcc, exec, s[44:45]
	s_cbranch_vccz .LBB0_113
	s_barrier

;     DI bool next(int i, Unit& u) const {
;         const long L = (long)i * G + c; const int nMz = nM * nZ, nwg = nMz * nN; if (L >= nwg) return false;
;         int wgid = (int)L; { const int q = nwg / NXCD, r = nwg % NXCD, xcd = wgid % NXCD, off = wgid / NXCD; wgid = (xcd < r ? xcd * (q + 1) : r * (q + 1) + (xcd - r) * q) + off; }
;         const int nig = WGM * nN, gid = wgid / nig, fm = gid * WGM, gsz = (nMz - fm) < WGM ? (nMz - fm) : WGM;
;         const int pmz = fm + ((wgid % nig) % gsz); u.pn = (wgid % nig) / gsz;
;         const int z = pmz / nM, pm = pmz - z * nM; u.pm = pm; u.z = z;
;         if (bmode == 0) u.b = B + (unsigned)z * sBz + (unsigned)u.pn * 256u * (unsigned)ldb2;
;         else if (bmode == 1) u.b = B + (unsigned)z * sBz + (unsigned)((u.pn >> 4) * 4096 + 4 * (u.pn & 15)) * (unsigned)ldb2;
;         else u.b = B + (unsigned)z * sBz + (unsigned)u.pn * 4u * 16384u;
;         if (mode == 0) { const unsigned a = A + (unsigned)z * sAz + (unsigned)pm * 256u * (unsigned)lda2; u.a0 = a; u.a1 = a + 64u * lda2; u.a2 = a + 128u * lda2; u.a3 = a + 192u * lda2; }
.LBB0_194:
	s_ashr_i32 s14, s40, 3
	s_add_i32 s14, s56, s14
	s_ashr_i32 s15, s14, 31
	s_lshr_b32 s15, s15, 26
	s_add_i32 s15, s14, s15
	s_ashr_i32 s40, s15, 6
	s_lshl_b32 s40, s40, 3
	s_sub_i32 s55, 0x80, s40
	s_min_i32 s56, s55, 8
	s_andn2_b32 s15, s15, 63
	s_sub_i32 s14, s14, s15
	s_nop 0
	s_lshr_b32 s55, s14, 3
	s_and_b32 s14, s14, 7
	s_add_i32 s14, s40, s14
	s_ashr_i32 s15, s14, 31
	s_lshr_b32 s15, s15, 25
	s_add_i32 s15, s14, s15
	s_and_b32 s15, s15, 0xffffff80
	s_mul_i32 s57, s21, s55
	s_sub_i32 s56, s14, s15
	v_readlane_b32 s14, v254, 49
	s_add_i32 s57, s57, s14
	s_mul_i32 s14, s21, s56
	s_add_i32 s61, s14, s19
	s_add_i32 s60, s61, s24
	s_add_i32 s59, s60, s24
	s_add_i32 s58, s59, s24
	s_mov_b32 s15, s61
	s_mov_b32 s67, s60
	s_mov_b32 s68, s59
	s_mov_b32 s69, s58
	s_mov_b32 s70, s57

; #define G_STAGE_A(bufoff, p0, p1, koff) do { \
;         __builtin_amdgcn_global_load_lds((const unsigned*)(gbase + (size_t)(unsigned)((p0) + (koff) + voffA[0])), (LAS unsigned*)(lds + (bufoff) + ldsw), 16, 0, 0); \
;         __builtin_amdgcn_global_load_lds((const unsigned*)(gbase + (size_t)(unsigned)((p1) + (koff) + voffA[1])), (LAS unsigned*)(lds + (bufoff) + ldsw + 8192), 16, 0, 0); } while (0)
; #define G_STAGE_B(bufoff, p, koff) do { \
;         __builtin_amdgcn_global_load_lds((const unsigned*)(gbase + (size_t)(unsigned)((p) + (koff) + voffB[0])), (LAS unsigned*)(lds + (bufoff) + ldsw), 16, 0, 0); \
;         __builtin_amdgcn_global_load_lds((const unsigned*)(gbase + (size_t)(unsigned)((p) + (koff) + voffB[1])), (LAS unsigned*)(lds + (bufoff) + ldsw + 8192), 16, 0, 0); } while (0)
; #define G_LDA(dst, b, h) do { _Pragma("unroll") for (int m = 0; m < 4; ++m) _Pragma("unroll") for (int k = 0; k < 2; ++k) dst[m][k] = *(const LAS bf16x8*)(lds + G_SA(b, h) + aoff + m * 2048 + k * 1024); } while (0)
; #define G_LDB(dst, b, h) do { _Pragma("unroll") for (int n = 0; n < 2; ++n) _Pragma("unroll") for (int k = 0; k < 2; ++k) dst[n][k] = *(const LAS bf16x8*)(lds + G_SB(b, h) + boff + n * 2048 + k * 1024); } while (0)
; #define G_WAIT_V(n) asm volatile("s_waitcnt vmcnt(" #n ")" ::: "memory")
; #define G_WAIT_L(n) asm volatile("s_waitcnt lgkmcnt(" #n ")" ::: "memory")
; template <class Epi>
; DI void gemm_phase(LAS unsigned char* lds, const Sched& S, const Epi& E, const int K) {
;     ...
;             const unsigned k1 = (unsigned)(t + 1) * kstepA;
;             const unsigned k2 = last ? 0u : (unsigned)(t + 2) * kstepA, k3 = k2 + kstepA;
;             const unsigned kb2 = last ? 0u : (unsigned)(t + 2) * kstepB, kb3 = kb2 + kstepB;
;             const unsigned x0 = last ? n0 : cur.a0, x1 = last ? n1 : cur.a1, x2 = last ? n2 : cur.a2, x3 = last ? n3 : cur.a3;
;             const unsigned xb = last ? nB : cur.b;
;     ...
;             G_LDB(B0, 0, 0); G_LDB(B1, 0, 1); G_SCHED; G_LDA(At, 0, 0); G_STAGE_A(G_SA(1, 1), cur.a2, cur.a3, k1);
;             G_WAIT_V(8); G_WAIT_L(0); G_BAR; G_MMA(0, 0, At, B0); G_MMA(0, 1, At, B1); G_BAR; G_SCHED;
;             G_LDA(At, 0, 1); G_STAGE_B(G_SB(0, 0), xb, kb2); G_STAGE_B(G_SB(0, 1), xb + hstepB, kb2); G_STAGE_A(G_SA(0, 0), x0, x1, k2);
;             G_WAIT_V(8); G_WAIT_L(0); G_BAR; G_MMA(1, 0, At, B0); G_MMA(1, 1, At, B1); G_BAR; G_SCHED;
.LBB0_196:
	s_add_i32 s72, s71, 2
	s_add_i32 s73, s14, 0x100
	s_cmp_eq_u32 s47, s71
	s_cselect_b32 s40, 0, s73
	s_cselect_b32 s78, s67, s37
	s_cselect_b32 s79, s69, s35
	s_cselect_b32 s80, s68, s36
	s_cselect_b32 s81, s15, s27
	s_cselect_b32 s75, s70, s26
	s_add_i32 s86, 0, 0x10000
	s_add_i32 s87, 0, 0x14000
	v_add_u32_e32 v152, s86, v133
	v_add_u32_e32 v168, s87, v133
	ds_read_b128 v[140:143], v152
	ds_read_b128 v[144:147], v152 offset:1024
	ds_read_b128 v[148:151], v152 offset:2048
	ds_read_b128 v[152:155], v152 offset:3072
	ds_read_b128 v[156:159], v168
	ds_read_b128 v[160:163], v168 offset:1024
	ds_read_b128 v[164:167], v168 offset:2048
	ds_read_b128 v[168:171], v168 offset:3072
	s_or_b32 s71, s40, 0x80
	v_add_u32_e32 v184, s14, v139
	s_add_i32 m0, s25, 0xc000
	ds_read_b128 v[172:175], v137
	ds_read_b128 v[176:179], v137 offset:1024
	ds_read_b128 v[180:183], v137 offset:2048
	ds_read_b128 v[194:197], v137 offset:3072
	ds_read_b128 v[198:201], v137 offset:4096
	ds_read_b128 v[202:205], v137 offset:5120
	ds_read_b128 v[206:209], v137 offset:6144
	ds_read_b128 v[210:213], v137 offset:7168
	global_load_lds_dwordx4 v184, s[82:83]
	v_add_u32_e32 v184, s14, v138
	s_add_i32 m0, s25, 0xe000
	s_nop 0
	global_load_lds_dwordx4 v184, s[82:83]
	s_add_i32 s14, s40, s75
	s_add_i32 s86, s86, s20
	v_add_u32_e32 v184, s14, v128
	s_mov_b32 m0, s86
	s_waitcnt vmcnt(8) lgkmcnt(0)
	s_barrier
	s_setprio 1
	v_mfma_f32_16x16x32_bf16 v[124:127], v[140:143], v[172:175], v[124:127]
	v_mfma_f32_16x16x32_bf16 v[120:123], v[148:151], v[172:175], v[120:123]
	v_mfma_f32_16x16x32_bf16 v[116:119], v[140:143], v[180:183], v[116:119]
	v_mfma_f32_16x16x32_bf16 v[112:115], v[148:151], v[180:183], v[112:115]
	v_mfma_f32_16x16x32_bf16 v[108:111], v[140:143], v[198:201], v[108:111]
	v_mfma_f32_16x16x32_bf16 v[104:107], v[148:151], v[198:201], v[104:107]
	v_mfma_f32_16x16x32_bf16 v[100:103], v[140:143], v[206:209], v[100:103]
	v_mfma_f32_16x16x32_bf16 v[96:99], v[148:151], v[206:209], v[96:99]
	v_mfma_f32_16x16x32_bf16 v[124:127], v[144:147], v[176:179], v[124:127]
	v_mfma_f32_16x16x32_bf16 v[120:123], v[152:155], v[176:179], v[120:123]
	v_mfma_f32_16x16x32_bf16 v[116:119], v[144:147], v[194:197], v[116:119]
	v_mfma_f32_16x16x32_bf16 v[112:115], v[152:155], v[194:197], v[112:115]
	v_mfma_f32_16x16x32_bf16 v[108:111], v[144:147], v[202:205], v[108:111]
	v_mfma_f32_16x16x32_bf16 v[104:107], v[152:155], v[202:205], v[104:107]
	v_mfma_f32_16x16x32_bf16 v[100:103], v[144:147], v[210:213], v[100:103]
	v_mfma_f32_16x16x32_bf16 v[96:99], v[152:155], v[210:213], v[96:99]
	v_mfma_f32_16x16x32_bf16 v[92:95], v[156:159], v[172:175], v[92:95]
	v_mfma_f32_16x16x32_bf16 v[88:91], v[164:167], v[172:175], v[88:91]
	v_mfma_f32_16x16x32_bf16 v[84:87], v[156:159], v[180:183], v[84:87]
	v_mfma_f32_16x16x32_bf16 v[80:83], v[164:167], v[180:183], v[80:83]
	v_mfma_f32_16x16x32_bf16 v[76:79], v[156:159], v[198:201], v[76:79]
	v_mfma_f32_16x16x32_bf16 v[72:75], v[164:167], v[198:201], v[72:75]
	v_mfma_f32_16x16x32_bf16 v[68:71], v[156:159], v[206:209], v[68:71]
	v_mfma_f32_16x16x32_bf16 v[64:67], v[164:167], v[206:209], v[64:67]
	v_mfma_f32_16x16x32_bf16 v[92:95], v[160:163], v[176:179], v[92:95]
	v_mfma_f32_16x16x32_bf16 v[88:91], v[168:171], v[176:179], v[88:91]
	v_mfma_f32_16x16x32_bf16 v[84:87], v[160:163], v[194:197], v[84:87]
	v_mfma_f32_16x16x32_bf16 v[80:83], v[168:171], v[194:197], v[80:83]
	v_mfma_f32_16x16x32_bf16 v[76:79], v[160:163], v[202:205], v[76:79]
	v_mfma_f32_16x16x32_bf16 v[72:75], v[168:171], v[202:205], v[72:75]
	v_mfma_f32_16x16x32_bf16 v[68:71], v[160:163], v[210:213], v[68:71]
	v_mfma_f32_16x16x32_bf16 v[64:67], v[168:171], v[210:213], v[64:67]
	s_setprio 0
	s_barrier
	ds_read_b128 v[172:175], v137 offset:16384
	ds_read_b128 v[176:179], v137 offset:17408
	ds_read_b128 v[180:183], v137 offset:18432
	ds_read_b128 v[194:197], v137 offset:19456
	ds_read_b128 v[198:201], v137 offset:20480
	ds_read_b128 v[202:205], v137 offset:21504
	ds_read_b128 v[206:209], v137 offset:22528
	ds_read_b128 v[210:213], v137 offset:23552
	global_load_lds_dwordx4 v184, s[82:83]
	v_add_u32_e32 v184, s14, v130
	s_add_i32 s14, s75, s16
	s_add_i32 m0, s86, 0x2000
	s_add_i32 s86, s14, s40
	s_add_i32 s87, s87, s20
	global_load_lds_dwordx4 v184, s[82:83]
	v_add_u32_e32 v184, s86, v128
	s_mov_b32 m0, s87
	s_nop 0
	global_load_lds_dwordx4 v184, s[82:83]
	v_add_u32_e32 v184, s86, v130
	s_add_i32 m0, s87, 0x2000
	s_nop 0
	global_load_lds_dwordx4 v184, s[82:83]
	v_add_u32_e32 v184, s81, v132
	v_add_u32_e32 v214, s40, v184
	s_mov_b32 m0, s25
	s_nop 0
	global_load_lds_dwordx4 v214, s[82:83]
	v_add_u32_e32 v214, s78, v129
	v_add_u32_e32 v215, s40, v214
	s_mov_b32 m0, s38
	s_nop 0
	global_load_lds_dwordx4 v215, s[82:83]
	s_waitcnt vmcnt(8) lgkmcnt(0)
	s_barrier
; #define G_STAGE_A(bufoff, p0, p1, koff) do { \
;         __builtin_amdgcn_global_load_lds((const unsigned*)(gbase + (size_t)(unsigned)((p0) + (koff) + voffA[0])), (LAS unsigned*)(lds + (bufoff) + ldsw), 16, 0, 0); \
;         __builtin_amdgcn_global_load_lds((const unsigned*)(gbase + (size_t)(unsigned)((p1) + (koff) + voffA[1])), (LAS unsigned*)(lds + (bufoff) + ldsw + 8192), 16, 0, 0); } while (0)
; #define G_LDA(dst, b, h) do { _Pragma("unroll") for (int m = 0; m < 4; ++m) _Pragma("unroll") for (int k = 0; k < 2; ++k) dst[m][k] = *(const LAS bf16x8*)(lds + G_SA(b, h) + aoff + m * 2048 + k * 1024); } while (0)
; #define G_LDB(dst, b, h) do { _Pragma("unroll") for (int n = 0; n < 2; ++n) _Pragma("unroll") for (int k = 0; k < 2; ++k) dst[n][k] = *(const LAS bf16x8*)(lds + G_SB(b, h) + boff + n * 2048 + k * 1024); } while (0)
; #define G_MMA(ai, bj, At, Bt) do { __builtin_amdgcn_s_setprio(1); _Pragma("unroll") for (int m = 0; m < 4; ++m) _Pragma("unroll") for (int n = 0; n < 2; ++n) _Pragma("unroll") for (int k = 0; k < 2; ++k) \
;         acc[ai][bj][m][n] = __builtin_amdgcn_mfma_f32_16x16x32_bf16(Bt[n][k], At[m][k], acc[ai][bj][m][n], 0, 0, 0); __builtin_amdgcn_s_setprio(0); } while (0)
; #define G_WAIT_V(n) asm volatile("s_waitcnt vmcnt(" #n ")" ::: "memory")
; #define G_WAIT_L(n) asm volatile("s_waitcnt lgkmcnt(" #n ")" ::: "memory")
; #define G_BAR __builtin_amdgcn_s_barrier()
; #define G_SCHED __builtin_amdgcn_sched_barrier(0)
; template <class Epi>
; DI void gemm_phase(LAS unsigned char* lds, const Sched& S, const Epi& E, const int K) {
;     ...
;             G_WAIT_V(8); G_WAIT_L(0); G_BAR; G_MMA(1, 0, At, B0); G_MMA(1, 1, At, B1); G_BAR; G_SCHED;
;             G_LDB(B0, 1, 0); G_LDB(B1, 1, 1); G_SCHED; G_LDA(At, 1, 0); G_STAGE_A(G_SA(0, 1), x2, x3, k2);
;             G_WAIT_V(8); G_WAIT_L(0); G_BAR; G_MMA(0, 0, At, B0); G_MMA(0, 1, At, B1); G_BAR; G_SCHED;
	s_setprio 1
	v_mfma_f32_16x16x32_bf16 v[60:63], v[140:143], v[172:175], v[60:63]
	v_mfma_f32_16x16x32_bf16 v[56:59], v[148:151], v[172:175], v[56:59]
	v_mfma_f32_16x16x32_bf16 v[52:55], v[140:143], v[180:183], v[52:55]
	v_mfma_f32_16x16x32_bf16 v[48:51], v[148:151], v[180:183], v[48:51]
	v_mfma_f32_16x16x32_bf16 v[44:47], v[140:143], v[198:201], v[44:47]
	v_mfma_f32_16x16x32_bf16 v[40:43], v[148:151], v[198:201], v[40:43]
	v_mfma_f32_16x16x32_bf16 v[36:39], v[140:143], v[206:209], v[36:39]
	v_mfma_f32_16x16x32_bf16 v[32:35], v[148:151], v[206:209], v[32:35]
	v_mfma_f32_16x16x32_bf16 v[60:63], v[144:147], v[176:179], v[60:63]
	v_mfma_f32_16x16x32_bf16 v[56:59], v[152:155], v[176:179], v[56:59]
	v_mfma_f32_16x16x32_bf16 v[52:55], v[144:147], v[194:197], v[52:55]
	v_mfma_f32_16x16x32_bf16 v[48:51], v[152:155], v[194:197], v[48:51]
	v_mfma_f32_16x16x32_bf16 v[44:47], v[144:147], v[202:205], v[44:47]
	v_mfma_f32_16x16x32_bf16 v[40:43], v[152:155], v[202:205], v[40:43]
	v_mfma_f32_16x16x32_bf16 v[36:39], v[144:147], v[210:213], v[36:39]
	v_mfma_f32_16x16x32_bf16 v[32:35], v[152:155], v[210:213], v[32:35]
	v_mfma_f32_16x16x32_bf16 v[28:31], v[156:159], v[172:175], v[28:31]
	v_mfma_f32_16x16x32_bf16 v[24:27], v[164:167], v[172:175], v[24:27]
	v_mfma_f32_16x16x32_bf16 v[20:23], v[156:159], v[180:183], v[20:23]
	v_mfma_f32_16x16x32_bf16 v[16:19], v[164:167], v[180:183], v[16:19]
	v_mfma_f32_16x16x32_bf16 v[12:15], v[156:159], v[198:201], v[12:15]
	v_mfma_f32_16x16x32_bf16 v[8:11], v[164:167], v[198:201], v[8:11]
	v_mfma_f32_16x16x32_bf16 v[4:7], v[156:159], v[206:209], v[4:7]
	v_mfma_f32_16x16x32_bf16 v[0:3], v[164:167], v[206:209], v[0:3]
	v_mfma_f32_16x16x32_bf16 v[28:31], v[160:163], v[176:179], v[28:31]
	v_mfma_f32_16x16x32_bf16 v[24:27], v[168:171], v[176:179], v[24:27]
	v_mfma_f32_16x16x32_bf16 v[20:23], v[160:163], v[194:197], v[20:23]
	v_mfma_f32_16x16x32_bf16 v[16:19], v[168:171], v[194:197], v[16:19]
	v_mfma_f32_16x16x32_bf16 v[12:15], v[160:163], v[202:205], v[12:15]
	v_mfma_f32_16x16x32_bf16 v[8:11], v[168:171], v[202:205], v[8:11]
	v_mfma_f32_16x16x32_bf16 v[4:7], v[160:163], v[210:213], v[4:7]
	v_mfma_f32_16x16x32_bf16 v[0:3], v[168:171], v[210:213], v[0:3]
	s_setprio 0
	s_barrier
	s_add_i32 s78, 0, 0x18000
	s_add_i32 s81, 0, 0x1c000
	v_add_u32_e32 v152, s78, v133
	v_add_u32_e32 v168, s81, v133
	ds_read_b128 v[140:143], v152
	ds_read_b128 v[144:147], v152 offset:1024
	ds_read_b128 v[148:151], v152 offset:2048
	ds_read_b128 v[152:155], v152 offset:3072
	ds_read_b128 v[156:159], v168
	ds_read_b128 v[160:163], v168 offset:1024
	ds_read_b128 v[164:167], v168 offset:2048
	ds_read_b128 v[168:171], v168 offset:3072
	s_add_i32 s80, s80, s40
	s_mov_b32 m0, s39
	v_add_u32_e32 v215, s80, v132
	s_add_i32 s79, s79, s40
	ds_read_b128 v[172:175], v137 offset:32768
	ds_read_b128 v[176:179], v137 offset:33792
	ds_read_b128 v[180:183], v137 offset:34816
	ds_read_b128 v[194:197], v137 offset:35840
	ds_read_b128 v[198:201], v137 offset:36864
	ds_read_b128 v[202:205], v137 offset:37888
	ds_read_b128 v[206:209], v137 offset:38912
	ds_read_b128 v[210:213], v137 offset:39936
	global_load_lds_dwordx4 v215, s[82:83]
	v_add_u32_e32 v215, s79, v129
	s_mov_b32 m0, s41
	s_nop 0
	global_load_lds_dwordx4 v215, s[82:83]
	s_add_i32 s40, s71, s75
	s_add_i32 s75, s78, s20
	v_add_u32_e32 v215, s40, v128
	s_mov_b32 m0, s75
	s_waitcnt vmcnt(8) lgkmcnt(0)
	s_barrier
; #define G_STAGE_A(bufoff, p0, p1, koff) do { \
;         __builtin_amdgcn_global_load_lds((const unsigned*)(gbase + (size_t)(unsigned)((p0) + (koff) + voffA[0])), (LAS unsigned*)(lds + (bufoff) + ldsw), 16, 0, 0); \
;         __builtin_amdgcn_global_load_lds((const unsigned*)(gbase + (size_t)(unsigned)((p1) + (koff) + voffA[1])), (LAS unsigned*)(lds + (bufoff) + ldsw + 8192), 16, 0, 0); } while (0)
; #define G_STAGE_B(bufoff, p, koff) do { \
;         __builtin_amdgcn_global_load_lds((const unsigned*)(gbase + (size_t)(unsigned)((p) + (koff) + voffB[0])), (LAS unsigned*)(lds + (bufoff) + ldsw), 16, 0, 0); \
;         __builtin_amdgcn_global_load_lds((const unsigned*)(gbase + (size_t)(unsigned)((p) + (koff) + voffB[1])), (LAS unsigned*)(lds + (bufoff) + ldsw + 8192), 16, 0, 0); } while (0)
; #define G_LDA(dst, b, h) do { _Pragma("unroll") for (int m = 0; m < 4; ++m) _Pragma("unroll") for (int k = 0; k < 2; ++k) dst[m][k] = *(const LAS bf16x8*)(lds + G_SA(b, h) + aoff + m * 2048 + k * 1024); } while (0)
; #define G_MMA(ai, bj, At, Bt) do { __builtin_amdgcn_s_setprio(1); _Pragma("unroll") for (int m = 0; m < 4; ++m) _Pragma("unroll") for (int n = 0; n < 2; ++n) _Pragma("unroll") for (int k = 0; k < 2; ++k) \
;         acc[ai][bj][m][n] = __builtin_amdgcn_mfma_f32_16x16x32_bf16(Bt[n][k], At[m][k], acc[ai][bj][m][n], 0, 0, 0); __builtin_amdgcn_s_setprio(0); } while (0)
; #define G_WAIT_V(n) asm volatile("s_waitcnt vmcnt(" #n ")" ::: "memory")
; #define G_WAIT_L(n) asm volatile("s_waitcnt lgkmcnt(" #n ")" ::: "memory")
; #define G_BAR __builtin_amdgcn_s_barrier()
; #define G_SCHED __builtin_amdgcn_sched_barrier(0)
; template <class Epi>
; DI void gemm_phase(LAS unsigned char* lds, const Sched& S, const Epi& E, const int K) {
;     ...
;             G_WAIT_V(8); G_WAIT_L(0); G_BAR; G_MMA(0, 0, At, B0); G_MMA(0, 1, At, B1); G_BAR; G_SCHED;
;             G_LDA(At, 1, 1); G_STAGE_B(G_SB(1, 0), xb, kb3); G_STAGE_B(G_SB(1, 1), xb + hstepB, kb3); G_STAGE_A(G_SA(1, 0), x0, x1, k3);
;             G_WAIT_V(8); G_WAIT_L(0); G_BAR; G_MMA(1, 0, At, B0); G_MMA(1, 1, At, B1); G_BAR; G_SCHED;
	s_setprio 1
	v_mfma_f32_16x16x32_bf16 v[124:127], v[140:143], v[172:175], v[124:127]
	v_mfma_f32_16x16x32_bf16 v[120:123], v[148:151], v[172:175], v[120:123]
	v_mfma_f32_16x16x32_bf16 v[116:119], v[140:143], v[180:183], v[116:119]
	v_mfma_f32_16x16x32_bf16 v[112:115], v[148:151], v[180:183], v[112:115]
	v_mfma_f32_16x16x32_bf16 v[108:111], v[140:143], v[198:201], v[108:111]
	v_mfma_f32_16x16x32_bf16 v[104:107], v[148:151], v[198:201], v[104:107]
	v_mfma_f32_16x16x32_bf16 v[100:103], v[140:143], v[206:209], v[100:103]
	v_mfma_f32_16x16x32_bf16 v[96:99], v[148:151], v[206:209], v[96:99]
	v_mfma_f32_16x16x32_bf16 v[124:127], v[144:147], v[176:179], v[124:127]
	v_mfma_f32_16x16x32_bf16 v[120:123], v[152:155], v[176:179], v[120:123]
	v_mfma_f32_16x16x32_bf16 v[116:119], v[144:147], v[194:197], v[116:119]
	v_mfma_f32_16x16x32_bf16 v[112:115], v[152:155], v[194:197], v[112:115]
	v_mfma_f32_16x16x32_bf16 v[108:111], v[144:147], v[202:205], v[108:111]
	v_mfma_f32_16x16x32_bf16 v[104:107], v[152:155], v[202:205], v[104:107]
	v_mfma_f32_16x16x32_bf16 v[100:103], v[144:147], v[210:213], v[100:103]
	v_mfma_f32_16x16x32_bf16 v[96:99], v[152:155], v[210:213], v[96:99]
	v_mfma_f32_16x16x32_bf16 v[92:95], v[156:159], v[172:175], v[92:95]
	v_mfma_f32_16x16x32_bf16 v[88:91], v[164:167], v[172:175], v[88:91]
	v_mfma_f32_16x16x32_bf16 v[84:87], v[156:159], v[180:183], v[84:87]
	v_mfma_f32_16x16x32_bf16 v[80:83], v[164:167], v[180:183], v[80:83]
	v_mfma_f32_16x16x32_bf16 v[76:79], v[156:159], v[198:201], v[76:79]
	v_mfma_f32_16x16x32_bf16 v[72:75], v[164:167], v[198:201], v[72:75]
	v_mfma_f32_16x16x32_bf16 v[68:71], v[156:159], v[206:209], v[68:71]
	v_mfma_f32_16x16x32_bf16 v[64:67], v[164:167], v[206:209], v[64:67]
	v_mfma_f32_16x16x32_bf16 v[92:95], v[160:163], v[176:179], v[92:95]
	v_mfma_f32_16x16x32_bf16 v[88:91], v[168:171], v[176:179], v[88:91]
	v_mfma_f32_16x16x32_bf16 v[84:87], v[160:163], v[194:197], v[84:87]
	v_mfma_f32_16x16x32_bf16 v[80:83], v[168:171], v[194:197], v[80:83]
	v_mfma_f32_16x16x32_bf16 v[76:79], v[160:163], v[202:205], v[76:79]
	v_mfma_f32_16x16x32_bf16 v[72:75], v[168:171], v[202:205], v[72:75]
	v_mfma_f32_16x16x32_bf16 v[68:71], v[160:163], v[210:213], v[68:71]
	v_mfma_f32_16x16x32_bf16 v[64:67], v[168:171], v[210:213], v[64:67]
	s_setprio 0
	s_barrier
	ds_read_b128 v[172:175], v137 offset:49152
	ds_read_b128 v[176:179], v137 offset:50176
	ds_read_b128 v[180:183], v137 offset:51200
	ds_read_b128 v[194:197], v137 offset:52224
	ds_read_b128 v[198:201], v137 offset:53248
	ds_read_b128 v[202:205], v137 offset:54272
	ds_read_b128 v[206:209], v137 offset:55296
	ds_read_b128 v[210:213], v137 offset:56320
	global_load_lds_dwordx4 v215, s[82:83]
	v_add_u32_e32 v215, s40, v130
	s_add_i32 m0, s75, 0x2000
	s_add_i32 s14, s71, s14
	s_add_i32 s40, s81, s20
	global_load_lds_dwordx4 v215, s[82:83]
	v_add_u32_e32 v215, s14, v128
	s_mov_b32 m0, s40
	v_add_u32_e32 v184, s71, v184
	global_load_lds_dwordx4 v215, s[82:83]
	v_add_u32_e32 v215, s14, v130
	s_add_i32 m0, s40, 0x2000
	s_nop 0
	global_load_lds_dwordx4 v215, s[82:83]
	s_mov_b32 m0, s45
	s_nop 0
	global_load_lds_dwordx4 v184, s[82:83]
	v_add_u32_e32 v184, s71, v214
	s_mov_b32 m0, s46
	s_nop 0
	global_load_lds_dwordx4 v184, s[82:83]
	s_waitcnt vmcnt(8) lgkmcnt(0)
	s_barrier
	s_setprio 1
	v_mfma_f32_16x16x32_bf16 v[60:63], v[140:143], v[172:175], v[60:63]
	v_mfma_f32_16x16x32_bf16 v[56:59], v[148:151], v[172:175], v[56:59]
	v_mfma_f32_16x16x32_bf16 v[52:55], v[140:143], v[180:183], v[52:55]
	v_mfma_f32_16x16x32_bf16 v[48:51], v[148:151], v[180:183], v[48:51]
	v_mfma_f32_16x16x32_bf16 v[44:47], v[140:143], v[198:201], v[44:47]
	v_mfma_f32_16x16x32_bf16 v[40:43], v[148:151], v[198:201], v[40:43]
	v_mfma_f32_16x16x32_bf16 v[36:39], v[140:143], v[206:209], v[36:39]
	v_mfma_f32_16x16x32_bf16 v[32:35], v[148:151], v[206:209], v[32:35]
	v_mfma_f32_16x16x32_bf16 v[60:63], v[144:147], v[176:179], v[60:63]
	v_mfma_f32_16x16x32_bf16 v[56:59], v[152:155], v[176:179], v[56:59]
	v_mfma_f32_16x16x32_bf16 v[52:55], v[144:147], v[194:197], v[52:55]
	v_mfma_f32_16x16x32_bf16 v[48:51], v[152:155], v[194:197], v[48:51]
	v_mfma_f32_16x16x32_bf16 v[44:47], v[144:147], v[202:205], v[44:47]
	v_mfma_f32_16x16x32_bf16 v[40:43], v[152:155], v[202:205], v[40:43]
	v_mfma_f32_16x16x32_bf16 v[36:39], v[144:147], v[210:213], v[36:39]
	v_mfma_f32_16x16x32_bf16 v[32:35], v[152:155], v[210:213], v[32:35]
	v_mfma_f32_16x16x32_bf16 v[28:31], v[156:159], v[172:175], v[28:31]
	v_mfma_f32_16x16x32_bf16 v[24:27], v[164:167], v[172:175], v[24:27]
	v_mfma_f32_16x16x32_bf16 v[20:23], v[156:159], v[180:183], v[20:23]
	v_mfma_f32_16x16x32_bf16 v[16:19], v[164:167], v[180:183], v[16:19]
	v_mfma_f32_16x16x32_bf16 v[12:15], v[156:159], v[198:201], v[12:15]
	v_mfma_f32_16x16x32_bf16 v[8:11], v[164:167], v[198:201], v[8:11]
	v_mfma_f32_16x16x32_bf16 v[4:7], v[156:159], v[206:209], v[4:7]
	v_mfma_f32_16x16x32_bf16 v[0:3], v[164:167], v[206:209], v[0:3]
	v_mfma_f32_16x16x32_bf16 v[28:31], v[160:163], v[176:179], v[28:31]
	v_mfma_f32_16x16x32_bf16 v[24:27], v[168:171], v[176:179], v[24:27]
	v_mfma_f32_16x16x32_bf16 v[20:23], v[160:163], v[194:197], v[20:23]
	v_mfma_f32_16x16x32_bf16 v[16:19], v[168:171], v[194:197], v[16:19]
	v_mfma_f32_16x16x32_bf16 v[12:15], v[160:163], v[202:205], v[12:15]
	v_mfma_f32_16x16x32_bf16 v[8:11], v[168:171], v[202:205], v[8:11]
	v_mfma_f32_16x16x32_bf16 v[4:7], v[160:163], v[210:213], v[4:7]
	v_mfma_f32_16x16x32_bf16 v[0:3], v[168:171], v[210:213], v[0:3]
	s_setprio 0
	s_barrier
	s_cmp_ge_u32 s72, s44
	s_mov_b32 s14, s73
	s_mov_b32 s71, s72
	s_cbranch_scc0 .LBB0_196
	s_and_b64 vcc, exec, s[12:13]
	s_mov_b32 s71, 0xf800000
	s_cbranch_vccz .LBB0_199
	s_barrier

;     DI bool next(int i, Unit& u) const {
;         const long L = (long)i * G + c; const int nMz = nM * nZ, nwg = nMz * nN; if (L >= nwg) return false;
;         int wgid = (int)L; { const int q = nwg / NXCD, r = nwg % NXCD, xcd = wgid % NXCD, off = wgid / NXCD; wgid = (xcd < r ? xcd * (q + 1) : r * (q + 1) + (xcd - r) * q) + off; }
;         const int nig = WGM * nN, gid = wgid / nig, fm = gid * WGM, gsz = (nMz - fm) < WGM ? (nMz - fm) : WGM;
;         const int pmz = fm + ((wgid % nig) % gsz); u.pn = (wgid % nig) / gsz;
;         const int z = pmz / nM, pm = pmz - z * nM; u.pm = pm; u.z = z;
;         if (bmode == 0) u.b = B + (unsigned)z * sBz + (unsigned)u.pn * 256u * (unsigned)ldb2;
;         else if (bmode == 1) u.b = B + (unsigned)z * sBz + (unsigned)((u.pn >> 4) * 4096 + 4 * (u.pn & 15)) * (unsigned)ldb2;
;         else u.b = B + (unsigned)z * sBz + (unsigned)u.pn * 4u * 16384u;
;         if (mode == 0) { const unsigned a = A + (unsigned)z * sAz + (unsigned)pm * 256u * (unsigned)lda2; u.a0 = a; u.a1 = a + 64u * lda2; u.a2 = a + 128u * lda2; u.a3 = a + 192u * lda2; }
.LBB0_215:
	s_ashr_i32 s13, s13, 3
	s_add_i32 s13, s54, s13
	s_ashr_i32 s14, s13, 31
	s_lshr_b32 s14, s14, 26
	s_add_i32 s14, s13, s14
	s_ashr_i32 s15, s14, 6
	s_lshl_b32 s15, s15, 3
	s_sub_i32 s40, 32, s15
	s_min_i32 s40, s40, 8
	s_andn2_b32 s14, s14, 63
	s_sub_i32 s13, s13, s14
	s_nop 0
	s_lshr_b32 s54, s13, 3
	s_and_b32 s13, s13, 7
	s_add_i32 s13, s15, s13
	s_ashr_i32 s14, s13, 31
	s_lshr_b32 s14, s14, 29
	s_add_i32 s14, s13, s14
	s_ashr_i32 s55, s14, 3
	s_and_b32 s14, s14, -8
	s_sub_i32 s56, s13, s14
	s_mul_i32 s14, s24, s54
	v_readlane_b32 s15, v254, 49
	s_mul_i32 s13, s55, s20
	s_add_i32 s14, s14, s15
	s_add_i32 s57, s14, s13
	s_add_i32 s13, s13, s19
	s_mul_i32 s14, s24, s56
	s_add_i32 s61, s13, s14
	s_add_i32 s60, s61, s25
	s_add_i32 s59, s60, s25
	s_add_i32 s58, s59, s25
	s_mov_b32 s13, s61
	s_mov_b32 s15, s60
	s_mov_b32 s67, s59
	s_mov_b32 s68, s58
	s_mov_b32 s69, s57

; #define G_STAGE_A(bufoff, p0, p1, koff) do { \
;         __builtin_amdgcn_global_load_lds((const unsigned*)(gbase + (size_t)(unsigned)((p0) + (koff) + voffA[0])), (LAS unsigned*)(lds + (bufoff) + ldsw), 16, 0, 0); \
;         __builtin_amdgcn_global_load_lds((const unsigned*)(gbase + (size_t)(unsigned)((p1) + (koff) + voffA[1])), (LAS unsigned*)(lds + (bufoff) + ldsw + 8192), 16, 0, 0); } while (0)
; #define G_STAGE_B(bufoff, p, koff) do { \
;         __builtin_amdgcn_global_load_lds((const unsigned*)(gbase + (size_t)(unsigned)((p) + (koff) + voffB[0])), (LAS unsigned*)(lds + (bufoff) + ldsw), 16, 0, 0); \
;         __builtin_amdgcn_global_load_lds((const unsigned*)(gbase + (size_t)(unsigned)((p) + (koff) + voffB[1])), (LAS unsigned*)(lds + (bufoff) + ldsw + 8192), 16, 0, 0); } while (0)
; #define G_LDA(dst, b, h) do { _Pragma("unroll") for (int m = 0; m < 4; ++m) _Pragma("unroll") for (int k = 0; k < 2; ++k) dst[m][k] = *(const LAS bf16x8*)(lds + G_SA(b, h) + aoff + m * 2048 + k * 1024); } while (0)
; #define G_LDB(dst, b, h) do { _Pragma("unroll") for (int n = 0; n < 2; ++n) _Pragma("unroll") for (int k = 0; k < 2; ++k) dst[n][k] = *(const LAS bf16x8*)(lds + G_SB(b, h) + boff + n * 2048 + k * 1024); } while (0)
; #define G_WAIT_V(n) asm volatile("s_waitcnt vmcnt(" #n ")" ::: "memory")
; #define G_WAIT_L(n) asm volatile("s_waitcnt lgkmcnt(" #n ")" ::: "memory")
; template <class Epi>
; DI void gemm_phase(LAS unsigned char* lds, const Sched& S, const Epi& E, const int K) {
;     ...
;             const unsigned k1 = (unsigned)(t + 1) * kstepA;
;             const unsigned k2 = last ? 0u : (unsigned)(t + 2) * kstepA, k3 = k2 + kstepA;
;             const unsigned kb2 = last ? 0u : (unsigned)(t + 2) * kstepB, kb3 = kb2 + kstepB;
;             const unsigned x0 = last ? n0 : cur.a0, x1 = last ? n1 : cur.a1, x2 = last ? n2 : cur.a2, x3 = last ? n3 : cur.a3;
;             const unsigned xb = last ? nB : cur.b;
;     ...
;             G_LDB(B0, 0, 0); G_LDB(B1, 0, 1); G_SCHED; G_LDA(At, 0, 0); G_STAGE_A(G_SA(1, 1), cur.a2, cur.a3, k1);
;             G_WAIT_V(8); G_WAIT_L(0); G_BAR; G_MMA(0, 0, At, B0); G_MMA(0, 1, At, B1); G_BAR; G_SCHED;
;             G_LDA(At, 0, 1); G_STAGE_B(G_SB(0, 0), xb, kb2); G_STAGE_B(G_SB(0, 1), xb + hstepB, kb2); G_STAGE_A(G_SA(0, 0), x0, x1, k2);
;             G_WAIT_V(8); G_WAIT_L(0); G_BAR; G_MMA(1, 0, At, B0); G_MMA(1, 1, At, B1); G_BAR; G_SCHED;
.LBB0_217:
	s_add_i32 s71, s70, 2
	s_add_i32 s72, s14, 0x100
	s_cmp_eq_u32 s46, s70
	s_cselect_b32 s40, 0, s72
	s_cselect_b32 s75, s15, s38
	s_cselect_b32 s78, s68, s36
	s_cselect_b32 s79, s67, s37
	s_cselect_b32 s80, s13, s35
	s_cselect_b32 s73, s69, s27
	s_add_i32 s81, 0, 0x10000
	s_add_i32 s86, 0, 0x14000
	v_add_u32_e32 v152, s81, v133
	v_add_u32_e32 v168, s86, v133
	ds_read_b128 v[140:143], v152
	ds_read_b128 v[144:147], v152 offset:1024
	ds_read_b128 v[148:151], v152 offset:2048
	ds_read_b128 v[152:155], v152 offset:3072
	ds_read_b128 v[156:159], v168
	ds_read_b128 v[160:163], v168 offset:1024
	ds_read_b128 v[164:167], v168 offset:2048
	ds_read_b128 v[168:171], v168 offset:3072
	s_or_b32 s70, s40, 0x80
	v_add_u32_e32 v184, s14, v139
	s_add_i32 m0, s26, 0xc000
	ds_read_b128 v[172:175], v137
	ds_read_b128 v[176:179], v137 offset:1024
	ds_read_b128 v[180:183], v137 offset:2048
	ds_read_b128 v[194:197], v137 offset:3072
	ds_read_b128 v[198:201], v137 offset:4096
	ds_read_b128 v[202:205], v137 offset:5120
	ds_read_b128 v[206:209], v137 offset:6144
	ds_read_b128 v[210:213], v137 offset:7168
	global_load_lds_dwordx4 v184, s[82:83]
	v_add_u32_e32 v184, s14, v138
	s_add_i32 m0, s26, 0xe000
	s_nop 0
	global_load_lds_dwordx4 v184, s[82:83]
	s_add_i32 s14, s40, s73
	s_add_i32 s81, s81, s21
	v_add_u32_e32 v184, s14, v128
	s_mov_b32 m0, s81
	s_waitcnt vmcnt(8) lgkmcnt(0)
	s_barrier
	s_setprio 1
	v_mfma_f32_16x16x32_bf16 v[124:127], v[140:143], v[172:175], v[124:127]
	v_mfma_f32_16x16x32_bf16 v[120:123], v[148:151], v[172:175], v[120:123]
	v_mfma_f32_16x16x32_bf16 v[116:119], v[140:143], v[180:183], v[116:119]
	v_mfma_f32_16x16x32_bf16 v[112:115], v[148:151], v[180:183], v[112:115]
	v_mfma_f32_16x16x32_bf16 v[108:111], v[140:143], v[198:201], v[108:111]
	v_mfma_f32_16x16x32_bf16 v[104:107], v[148:151], v[198:201], v[104:107]
	v_mfma_f32_16x16x32_bf16 v[100:103], v[140:143], v[206:209], v[100:103]
	v_mfma_f32_16x16x32_bf16 v[96:99], v[148:151], v[206:209], v[96:99]
	v_mfma_f32_16x16x32_bf16 v[124:127], v[144:147], v[176:179], v[124:127]
	v_mfma_f32_16x16x32_bf16 v[120:123], v[152:155], v[176:179], v[120:123]
	v_mfma_f32_16x16x32_bf16 v[116:119], v[144:147], v[194:197], v[116:119]
	v_mfma_f32_16x16x32_bf16 v[112:115], v[152:155], v[194:197], v[112:115]
	v_mfma_f32_16x16x32_bf16 v[108:111], v[144:147], v[202:205], v[108:111]
	v_mfma_f32_16x16x32_bf16 v[104:107], v[152:155], v[202:205], v[104:107]
	v_mfma_f32_16x16x32_bf16 v[100:103], v[144:147], v[210:213], v[100:103]
	v_mfma_f32_16x16x32_bf16 v[96:99], v[152:155], v[210:213], v[96:99]
	v_mfma_f32_16x16x32_bf16 v[92:95], v[156:159], v[172:175], v[92:95]
	v_mfma_f32_16x16x32_bf16 v[88:91], v[164:167], v[172:175], v[88:91]
	v_mfma_f32_16x16x32_bf16 v[84:87], v[156:159], v[180:183], v[84:87]
	v_mfma_f32_16x16x32_bf16 v[80:83], v[164:167], v[180:183], v[80:83]
	v_mfma_f32_16x16x32_bf16 v[76:79], v[156:159], v[198:201], v[76:79]
	v_mfma_f32_16x16x32_bf16 v[72:75], v[164:167], v[198:201], v[72:75]
	v_mfma_f32_16x16x32_bf16 v[68:71], v[156:159], v[206:209], v[68:71]
	v_mfma_f32_16x16x32_bf16 v[64:67], v[164:167], v[206:209], v[64:67]
	v_mfma_f32_16x16x32_bf16 v[92:95], v[160:163], v[176:179], v[92:95]
	v_mfma_f32_16x16x32_bf16 v[88:91], v[168:171], v[176:179], v[88:91]
	v_mfma_f32_16x16x32_bf16 v[84:87], v[160:163], v[194:197], v[84:87]
	v_mfma_f32_16x16x32_bf16 v[80:83], v[168:171], v[194:197], v[80:83]
	v_mfma_f32_16x16x32_bf16 v[76:79], v[160:163], v[202:205], v[76:79]
	v_mfma_f32_16x16x32_bf16 v[72:75], v[168:171], v[202:205], v[72:75]
	v_mfma_f32_16x16x32_bf16 v[68:71], v[160:163], v[210:213], v[68:71]
	v_mfma_f32_16x16x32_bf16 v[64:67], v[168:171], v[210:213], v[64:67]
	s_setprio 0
	s_barrier
	ds_read_b128 v[172:175], v137 offset:16384
	ds_read_b128 v[176:179], v137 offset:17408
	ds_read_b128 v[180:183], v137 offset:18432
	ds_read_b128 v[194:197], v137 offset:19456
	ds_read_b128 v[198:201], v137 offset:20480
	ds_read_b128 v[202:205], v137 offset:21504
	ds_read_b128 v[206:209], v137 offset:22528
	ds_read_b128 v[210:213], v137 offset:23552
	global_load_lds_dwordx4 v184, s[82:83]
	v_add_u32_e32 v184, s14, v130
	s_add_i32 s14, s73, s16
	s_add_i32 m0, s81, 0x2000
	s_add_i32 s81, s14, s40
	s_add_i32 s86, s86, s21
	global_load_lds_dwordx4 v184, s[82:83]
	v_add_u32_e32 v184, s81, v128
	s_mov_b32 m0, s86
	s_nop 0
	global_load_lds_dwordx4 v184, s[82:83]
	v_add_u32_e32 v184, s81, v130
	s_add_i32 m0, s86, 0x2000
	s_nop 0
	global_load_lds_dwordx4 v184, s[82:83]
	v_add_u32_e32 v184, s80, v132
	v_add_u32_e32 v214, s40, v184
	s_mov_b32 m0, s26
	s_nop 0
	global_load_lds_dwordx4 v214, s[82:83]
	v_add_u32_e32 v214, s75, v129
	v_add_u32_e32 v215, s40, v214
	s_mov_b32 m0, s39
	s_nop 0
	global_load_lds_dwordx4 v215, s[82:83]
	s_waitcnt vmcnt(8) lgkmcnt(0)
	s_barrier
; #define G_STAGE_A(bufoff, p0, p1, koff) do { \
;         __builtin_amdgcn_global_load_lds((const unsigned*)(gbase + (size_t)(unsigned)((p0) + (koff) + voffA[0])), (LAS unsigned*)(lds + (bufoff) + ldsw), 16, 0, 0); \
;         __builtin_amdgcn_global_load_lds((const unsigned*)(gbase + (size_t)(unsigned)((p1) + (koff) + voffA[1])), (LAS unsigned*)(lds + (bufoff) + ldsw + 8192), 16, 0, 0); } while (0)
; #define G_LDA(dst, b, h) do { _Pragma("unroll") for (int m = 0; m < 4; ++m) _Pragma("unroll") for (int k = 0; k < 2; ++k) dst[m][k] = *(const LAS bf16x8*)(lds + G_SA(b, h) + aoff + m * 2048 + k * 1024); } while (0)
; #define G_LDB(dst, b, h) do { _Pragma("unroll") for (int n = 0; n < 2; ++n) _Pragma("unroll") for (int k = 0; k < 2; ++k) dst[n][k] = *(const LAS bf16x8*)(lds + G_SB(b, h) + boff + n * 2048 + k * 1024); } while (0)
; #define G_MMA(ai, bj, At, Bt) do { __builtin_amdgcn_s_setprio(1); _Pragma("unroll") for (int m = 0; m < 4; ++m) _Pragma("unroll") for (int n = 0; n < 2; ++n) _Pragma("unroll") for (int k = 0; k < 2; ++k) \
;         acc[ai][bj][m][n] = __builtin_amdgcn_mfma_f32_16x16x32_bf16(Bt[n][k], At[m][k], acc[ai][bj][m][n], 0, 0, 0); __builtin_amdgcn_s_setprio(0); } while (0)
; #define G_WAIT_V(n) asm volatile("s_waitcnt vmcnt(" #n ")" ::: "memory")
; #define G_WAIT_L(n) asm volatile("s_waitcnt lgkmcnt(" #n ")" ::: "memory")
; #define G_BAR __builtin_amdgcn_s_barrier()
; #define G_SCHED __builtin_amdgcn_sched_barrier(0)
; template <class Epi>
; DI void gemm_phase(LAS unsigned char* lds, const Sched& S, const Epi& E, const int K) {
;     ...
;             G_WAIT_V(8); G_WAIT_L(0); G_BAR; G_MMA(1, 0, At, B0); G_MMA(1, 1, At, B1); G_BAR; G_SCHED;
;             G_LDB(B0, 1, 0); G_LDB(B1, 1, 1); G_SCHED; G_LDA(At, 1, 0); G_STAGE_A(G_SA(0, 1), x2, x3, k2);
;             G_WAIT_V(8); G_WAIT_L(0); G_BAR; G_MMA(0, 0, At, B0); G_MMA(0, 1, At, B1); G_BAR; G_SCHED;
	s_setprio 1
	v_mfma_f32_16x16x32_bf16 v[60:63], v[140:143], v[172:175], v[60:63]
	v_mfma_f32_16x16x32_bf16 v[56:59], v[148:151], v[172:175], v[56:59]
	v_mfma_f32_16x16x32_bf16 v[52:55], v[140:143], v[180:183], v[52:55]
	v_mfma_f32_16x16x32_bf16 v[48:51], v[148:151], v[180:183], v[48:51]
	v_mfma_f32_16x16x32_bf16 v[44:47], v[140:143], v[198:201], v[44:47]
	v_mfma_f32_16x16x32_bf16 v[40:43], v[148:151], v[198:201], v[40:43]
	v_mfma_f32_16x16x32_bf16 v[36:39], v[140:143], v[206:209], v[36:39]
	v_mfma_f32_16x16x32_bf16 v[32:35], v[148:151], v[206:209], v[32:35]
	v_mfma_f32_16x16x32_bf16 v[60:63], v[144:147], v[176:179], v[60:63]
	v_mfma_f32_16x16x32_bf16 v[56:59], v[152:155], v[176:179], v[56:59]
	v_mfma_f32_16x16x32_bf16 v[52:55], v[144:147], v[194:197], v[52:55]
	v_mfma_f32_16x16x32_bf16 v[48:51], v[152:155], v[194:197], v[48:51]
	v_mfma_f32_16x16x32_bf16 v[44:47], v[144:147], v[202:205], v[44:47]
	v_mfma_f32_16x16x32_bf16 v[40:43], v[152:155], v[202:205], v[40:43]
	v_mfma_f32_16x16x32_bf16 v[36:39], v[144:147], v[210:213], v[36:39]
	v_mfma_f32_16x16x32_bf16 v[32:35], v[152:155], v[210:213], v[32:35]
	v_mfma_f32_16x16x32_bf16 v[28:31], v[156:159], v[172:175], v[28:31]
	v_mfma_f32_16x16x32_bf16 v[24:27], v[164:167], v[172:175], v[24:27]
	v_mfma_f32_16x16x32_bf16 v[20:23], v[156:159], v[180:183], v[20:23]
	v_mfma_f32_16x16x32_bf16 v[16:19], v[164:167], v[180:183], v[16:19]
	v_mfma_f32_16x16x32_bf16 v[12:15], v[156:159], v[198:201], v[12:15]
	v_mfma_f32_16x16x32_bf16 v[8:11], v[164:167], v[198:201], v[8:11]
	v_mfma_f32_16x16x32_bf16 v[4:7], v[156:159], v[206:209], v[4:7]
	v_mfma_f32_16x16x32_bf16 v[0:3], v[164:167], v[206:209], v[0:3]
	v_mfma_f32_16x16x32_bf16 v[28:31], v[160:163], v[176:179], v[28:31]
	v_mfma_f32_16x16x32_bf16 v[24:27], v[168:171], v[176:179], v[24:27]
	v_mfma_f32_16x16x32_bf16 v[20:23], v[160:163], v[194:197], v[20:23]
	v_mfma_f32_16x16x32_bf16 v[16:19], v[168:171], v[194:197], v[16:19]
	v_mfma_f32_16x16x32_bf16 v[12:15], v[160:163], v[202:205], v[12:15]
	v_mfma_f32_16x16x32_bf16 v[8:11], v[168:171], v[202:205], v[8:11]
	v_mfma_f32_16x16x32_bf16 v[4:7], v[160:163], v[210:213], v[4:7]
	v_mfma_f32_16x16x32_bf16 v[0:3], v[168:171], v[210:213], v[0:3]
	s_setprio 0
	s_barrier
	s_add_i32 s75, 0, 0x18000
	s_add_i32 s80, 0, 0x1c000
	v_add_u32_e32 v152, s75, v133
	v_add_u32_e32 v168, s80, v133
	ds_read_b128 v[140:143], v152
	ds_read_b128 v[144:147], v152 offset:1024
	ds_read_b128 v[148:151], v152 offset:2048
	ds_read_b128 v[152:155], v152 offset:3072
	ds_read_b128 v[156:159], v168
	ds_read_b128 v[160:163], v168 offset:1024
	ds_read_b128 v[164:167], v168 offset:2048
	ds_read_b128 v[168:171], v168 offset:3072
	s_add_i32 s79, s79, s40
	s_mov_b32 m0, s41
	v_add_u32_e32 v215, s79, v132
	s_add_i32 s78, s78, s40
	ds_read_b128 v[172:175], v137 offset:32768
	ds_read_b128 v[176:179], v137 offset:33792
	ds_read_b128 v[180:183], v137 offset:34816
	ds_read_b128 v[194:197], v137 offset:35840
	ds_read_b128 v[198:201], v137 offset:36864
	ds_read_b128 v[202:205], v137 offset:37888
	ds_read_b128 v[206:209], v137 offset:38912
	ds_read_b128 v[210:213], v137 offset:39936
	global_load_lds_dwordx4 v215, s[82:83]
	v_add_u32_e32 v215, s78, v129
	s_mov_b32 m0, s44
	s_nop 0
	global_load_lds_dwordx4 v215, s[82:83]
	s_add_i32 s40, s70, s73
	s_add_i32 s73, s75, s21
	v_add_u32_e32 v215, s40, v128
	s_mov_b32 m0, s73
	s_waitcnt vmcnt(8) lgkmcnt(0)
	s_barrier
; #define G_STAGE_A(bufoff, p0, p1, koff) do { \
;         __builtin_amdgcn_global_load_lds((const unsigned*)(gbase + (size_t)(unsigned)((p0) + (koff) + voffA[0])), (LAS unsigned*)(lds + (bufoff) + ldsw), 16, 0, 0); \
;         __builtin_amdgcn_global_load_lds((const unsigned*)(gbase + (size_t)(unsigned)((p1) + (koff) + voffA[1])), (LAS unsigned*)(lds + (bufoff) + ldsw + 8192), 16, 0, 0); } while (0)
; #define G_STAGE_B(bufoff, p, koff) do { \
;         __builtin_amdgcn_global_load_lds((const unsigned*)(gbase + (size_t)(unsigned)((p) + (koff) + voffB[0])), (LAS unsigned*)(lds + (bufoff) + ldsw), 16, 0, 0); \
;         __builtin_amdgcn_global_load_lds((const unsigned*)(gbase + (size_t)(unsigned)((p) + (koff) + voffB[1])), (LAS unsigned*)(lds + (bufoff) + ldsw + 8192), 16, 0, 0); } while (0)
; #define G_LDA(dst, b, h) do { _Pragma("unroll") for (int m = 0; m < 4; ++m) _Pragma("unroll") for (int k = 0; k < 2; ++k) dst[m][k] = *(const LAS bf16x8*)(lds + G_SA(b, h) + aoff + m * 2048 + k * 1024); } while (0)
; #define G_MMA(ai, bj, At, Bt) do { __builtin_amdgcn_s_setprio(1); _Pragma("unroll") for (int m = 0; m < 4; ++m) _Pragma("unroll") for (int n = 0; n < 2; ++n) _Pragma("unroll") for (int k = 0; k < 2; ++k) \
;         acc[ai][bj][m][n] = __builtin_amdgcn_mfma_f32_16x16x32_bf16(Bt[n][k], At[m][k], acc[ai][bj][m][n], 0, 0, 0); __builtin_amdgcn_s_setprio(0); } while (0)
; #define G_WAIT_V(n) asm volatile("s_waitcnt vmcnt(" #n ")" ::: "memory")
; #define G_WAIT_L(n) asm volatile("s_waitcnt lgkmcnt(" #n ")" ::: "memory")
; #define G_BAR __builtin_amdgcn_s_barrier()
; #define G_SCHED __builtin_amdgcn_sched_barrier(0)
; template <class Epi>
; DI void gemm_phase(LAS unsigned char* lds, const Sched& S, const Epi& E, const int K) {
;     ...
;             G_WAIT_V(8); G_WAIT_L(0); G_BAR; G_MMA(0, 0, At, B0); G_MMA(0, 1, At, B1); G_BAR; G_SCHED;
;             G_LDA(At, 1, 1); G_STAGE_B(G_SB(1, 0), xb, kb3); G_STAGE_B(G_SB(1, 1), xb + hstepB, kb3); G_STAGE_A(G_SA(1, 0), x0, x1, k3);
;             G_WAIT_V(8); G_WAIT_L(0); G_BAR; G_MMA(1, 0, At, B0); G_MMA(1, 1, At, B1); G_BAR; G_SCHED;
	s_setprio 1
	v_mfma_f32_16x16x32_bf16 v[124:127], v[140:143], v[172:175], v[124:127]
	v_mfma_f32_16x16x32_bf16 v[120:123], v[148:151], v[172:175], v[120:123]
	v_mfma_f32_16x16x32_bf16 v[116:119], v[140:143], v[180:183], v[116:119]
	v_mfma_f32_16x16x32_bf16 v[112:115], v[148:151], v[180:183], v[112:115]
	v_mfma_f32_16x16x32_bf16 v[108:111], v[140:143], v[198:201], v[108:111]
	v_mfma_f32_16x16x32_bf16 v[104:107], v[148:151], v[198:201], v[104:107]
	v_mfma_f32_16x16x32_bf16 v[100:103], v[140:143], v[206:209], v[100:103]
	v_mfma_f32_16x16x32_bf16 v[96:99], v[148:151], v[206:209], v[96:99]
	v_mfma_f32_16x16x32_bf16 v[124:127], v[144:147], v[176:179], v[124:127]
	v_mfma_f32_16x16x32_bf16 v[120:123], v[152:155], v[176:179], v[120:123]
	v_mfma_f32_16x16x32_bf16 v[116:119], v[144:147], v[194:197], v[116:119]
	v_mfma_f32_16x16x32_bf16 v[112:115], v[152:155], v[194:197], v[112:115]
	v_mfma_f32_16x16x32_bf16 v[108:111], v[144:147], v[202:205], v[108:111]
	v_mfma_f32_16x16x32_bf16 v[104:107], v[152:155], v[202:205], v[104:107]
	v_mfma_f32_16x16x32_bf16 v[100:103], v[144:147], v[210:213], v[100:103]
	v_mfma_f32_16x16x32_bf16 v[96:99], v[152:155], v[210:213], v[96:99]
	v_mfma_f32_16x16x32_bf16 v[92:95], v[156:159], v[172:175], v[92:95]
	v_mfma_f32_16x16x32_bf16 v[88:91], v[164:167], v[172:175], v[88:91]
	v_mfma_f32_16x16x32_bf16 v[84:87], v[156:159], v[180:183], v[84:87]
	v_mfma_f32_16x16x32_bf16 v[80:83], v[164:167], v[180:183], v[80:83]
	v_mfma_f32_16x16x32_bf16 v[76:79], v[156:159], v[198:201], v[76:79]
	v_mfma_f32_16x16x32_bf16 v[72:75], v[164:167], v[198:201], v[72:75]
	v_mfma_f32_16x16x32_bf16 v[68:71], v[156:159], v[206:209], v[68:71]
	v_mfma_f32_16x16x32_bf16 v[64:67], v[164:167], v[206:209], v[64:67]
	v_mfma_f32_16x16x32_bf16 v[92:95], v[160:163], v[176:179], v[92:95]
	v_mfma_f32_16x16x32_bf16 v[88:91], v[168:171], v[176:179], v[88:91]
	v_mfma_f32_16x16x32_bf16 v[84:87], v[160:163], v[194:197], v[84:87]
	v_mfma_f32_16x16x32_bf16 v[80:83], v[168:171], v[194:197], v[80:83]
	v_mfma_f32_16x16x32_bf16 v[76:79], v[160:163], v[202:205], v[76:79]
	v_mfma_f32_16x16x32_bf16 v[72:75], v[168:171], v[202:205], v[72:75]
	v_mfma_f32_16x16x32_bf16 v[68:71], v[160:163], v[210:213], v[68:71]
	v_mfma_f32_16x16x32_bf16 v[64:67], v[168:171], v[210:213], v[64:67]
	s_setprio 0
	s_barrier
	ds_read_b128 v[172:175], v137 offset:49152
	ds_read_b128 v[176:179], v137 offset:50176
	ds_read_b128 v[180:183], v137 offset:51200
	ds_read_b128 v[194:197], v137 offset:52224
	ds_read_b128 v[198:201], v137 offset:53248
	ds_read_b128 v[202:205], v137 offset:54272
	ds_read_b128 v[206:209], v137 offset:55296
	ds_read_b128 v[210:213], v137 offset:56320
	global_load_lds_dwordx4 v215, s[82:83]
	v_add_u32_e32 v215, s40, v130
	s_add_i32 m0, s73, 0x2000
	s_add_i32 s14, s70, s14
	s_add_i32 s40, s80, s21
	global_load_lds_dwordx4 v215, s[82:83]
	v_add_u32_e32 v215, s14, v128
	s_mov_b32 m0, s40
	v_add_u32_e32 v184, s70, v184
	global_load_lds_dwordx4 v215, s[82:83]
	v_add_u32_e32 v215, s14, v130
	s_add_i32 m0, s40, 0x2000
	s_nop 0
	global_load_lds_dwordx4 v215, s[82:83]
	s_mov_b32 m0, s18
	s_nop 0
	global_load_lds_dwordx4 v184, s[82:83]
	v_add_u32_e32 v184, s70, v214
	s_mov_b32 m0, s45
	s_nop 0
	global_load_lds_dwordx4 v184, s[82:83]
	s_waitcnt vmcnt(8) lgkmcnt(0)
	s_barrier
	s_setprio 1
	v_mfma_f32_16x16x32_bf16 v[60:63], v[140:143], v[172:175], v[60:63]
	v_mfma_f32_16x16x32_bf16 v[56:59], v[148:151], v[172:175], v[56:59]
	v_mfma_f32_16x16x32_bf16 v[52:55], v[140:143], v[180:183], v[52:55]
	v_mfma_f32_16x16x32_bf16 v[48:51], v[148:151], v[180:183], v[48:51]
	v_mfma_f32_16x16x32_bf16 v[44:47], v[140:143], v[198:201], v[44:47]
	v_mfma_f32_16x16x32_bf16 v[40:43], v[148:151], v[198:201], v[40:43]
	v_mfma_f32_16x16x32_bf16 v[36:39], v[140:143], v[206:209], v[36:39]
	v_mfma_f32_16x16x32_bf16 v[32:35], v[148:151], v[206:209], v[32:35]
	v_mfma_f32_16x16x32_bf16 v[60:63], v[144:147], v[176:179], v[60:63]
	v_mfma_f32_16x16x32_bf16 v[56:59], v[152:155], v[176:179], v[56:59]
	v_mfma_f32_16x16x32_bf16 v[52:55], v[144:147], v[194:197], v[52:55]
	v_mfma_f32_16x16x32_bf16 v[48:51], v[152:155], v[194:197], v[48:51]
	v_mfma_f32_16x16x32_bf16 v[44:47], v[144:147], v[202:205], v[44:47]
	v_mfma_f32_16x16x32_bf16 v[40:43], v[152:155], v[202:205], v[40:43]
	v_mfma_f32_16x16x32_bf16 v[36:39], v[144:147], v[210:213], v[36:39]
	v_mfma_f32_16x16x32_bf16 v[32:35], v[152:155], v[210:213], v[32:35]
	v_mfma_f32_16x16x32_bf16 v[28:31], v[156:159], v[172:175], v[28:31]
	v_mfma_f32_16x16x32_bf16 v[24:27], v[164:167], v[172:175], v[24:27]
	v_mfma_f32_16x16x32_bf16 v[20:23], v[156:159], v[180:183], v[20:23]
	v_mfma_f32_16x16x32_bf16 v[16:19], v[164:167], v[180:183], v[16:19]
	v_mfma_f32_16x16x32_bf16 v[12:15], v[156:159], v[198:201], v[12:15]
	v_mfma_f32_16x16x32_bf16 v[8:11], v[164:167], v[198:201], v[8:11]
	v_mfma_f32_16x16x32_bf16 v[4:7], v[156:159], v[206:209], v[4:7]
	v_mfma_f32_16x16x32_bf16 v[0:3], v[164:167], v[206:209], v[0:3]
	v_mfma_f32_16x16x32_bf16 v[28:31], v[160:163], v[176:179], v[28:31]
	v_mfma_f32_16x16x32_bf16 v[24:27], v[168:171], v[176:179], v[24:27]
	v_mfma_f32_16x16x32_bf16 v[20:23], v[160:163], v[194:197], v[20:23]
	v_mfma_f32_16x16x32_bf16 v[16:19], v[168:171], v[194:197], v[16:19]
	v_mfma_f32_16x16x32_bf16 v[12:15], v[160:163], v[202:205], v[12:15]
	v_mfma_f32_16x16x32_bf16 v[8:11], v[168:171], v[202:205], v[8:11]
	v_mfma_f32_16x16x32_bf16 v[4:7], v[160:163], v[210:213], v[4:7]
	v_mfma_f32_16x16x32_bf16 v[0:3], v[168:171], v[210:213], v[0:3]
	s_setprio 0
	s_barrier
	s_cmp_ge_u32 s71, s17
	s_mov_b32 s14, s72
	s_mov_b32 s70, s71
	s_cbranch_scc0 .LBB0_217
	s_and_b64 vcc, exec, s[10:11]
	s_movk_i32 s70, 0x1000
	s_cbranch_vccz .LBB0_220
	s_barrier

;     DI bool next(int i, Unit& u) const {
;         const long L = (long)i * G + c; const int nMz = nM * nZ, nwg = nMz * nN; if (L >= nwg) return false;
;         int wgid = (int)L; { const int q = nwg / NXCD, r = nwg % NXCD, xcd = wgid % NXCD, off = wgid / NXCD; wgid = (xcd < r ? xcd * (q + 1) : r * (q + 1) + (xcd - r) * q) + off; }
;         const int nig = WGM * nN, gid = wgid / nig, fm = gid * WGM, gsz = (nMz - fm) < WGM ? (nMz - fm) : WGM;
;         const int pmz = fm + ((wgid % nig) % gsz); u.pn = (wgid % nig) / gsz;
;         const int z = pmz / nM, pm = pmz - z * nM; u.pm = pm; u.z = z;
;         if (bmode == 0) u.b = B + (unsigned)z * sBz + (unsigned)u.pn * 256u * (unsigned)ldb2;
;         else if (bmode == 1) u.b = B + (unsigned)z * sBz + (unsigned)((u.pn >> 4) * 4096 + 4 * (u.pn & 15)) * (unsigned)ldb2;
;         else u.b = B + (unsigned)z * sBz + (unsigned)u.pn * 4u * 16384u;
.LBB0_239:
	s_ashr_i32 s14, s36, 3
	s_add_i32 s14, s38, s14
	s_ashr_i32 s15, s14, 31
	s_lshr_b32 s15, s15, 27
	s_add_i32 s15, s14, s15
	s_ashr_i32 s36, s15, 5
	s_lshl_b32 s37, s36, 3
	s_sub_i32 s36, 0x200, s37
	s_min_i32 s38, s36, 8
	s_andn2_b32 s15, s15, 31
	s_sub_i32 s14, s14, s15
	s_nop 0
	s_lshr_b32 s36, s14, 3
	s_and_b32 s14, s14, 7
	s_add_i32 s37, s37, s14
	s_lshl_b32 s14, s37, 18
	s_lshl_b32 s15, s36, 16
	s_add_i32 s14, s15, s14
	s_add_i32 s38, s14, 0x19000000
	s_mov_b32 s15, s38

;     DI bool next(int i, Unit& u) const {
;         const long L = (long)i * G + c; const int nMz = nM * nZ, nwg = nMz * nN; if (L >= nwg) return false;
;         int wgid = (int)L; { const int q = nwg / NXCD, r = nwg % NXCD, xcd = wgid % NXCD, off = wgid / NXCD; wgid = (xcd < r ? xcd * (q + 1) : r * (q + 1) + (xcd - r) * q) + off; }
;         const int nig = WGM * nN, gid = wgid / nig, fm = gid * WGM, gsz = (nMz - fm) < WGM ? (nMz - fm) : WGM;
;         const int pmz = fm + ((wgid % nig) % gsz); u.pn = (wgid % nig) / gsz;
;         const int z = pmz / nM, pm = pmz - z * nM; u.pm = pm; u.z = z;
;         if (bmode == 0) u.b = B + (unsigned)z * sBz + (unsigned)u.pn * 256u * (unsigned)ldb2;
;         else if (bmode == 1) u.b = B + (unsigned)z * sBz + (unsigned)((u.pn >> 4) * 4096 + 4 * (u.pn & 15)) * (unsigned)ldb2;
;         else u.b = B + (unsigned)z * sBz + (unsigned)u.pn * 4u * 16384u;
.LBB0_260:
	s_ashr_i32 s12, s14, 3
	s_add_i32 s12, s36, s12
	s_ashr_i32 s13, s12, 31
	s_lshr_b32 s13, s13, 21
	s_add_i32 s13, s12, s13
	s_ashr_i32 s14, s13, 11
	s_lshl_b32 s14, s14, 3
	s_sub_i32 s15, 8, s14
	s_min_i32 s15, s15, 8
	s_and_b32 s13, s13, 0xfffff800
	s_sub_i32 s12, s12, s13
	s_nop 0
	s_lshr_b32 s36, s12, 3
	s_and_b32 s12, s12, 7
	s_add_i32 s37, s14, s12
	s_lshl_b32 s12, s37, 24
	s_lshl_b32 s13, s36, 16
	s_add_i32 s12, s13, s12
	s_add_i32 s38, s12, 0x2a000000
	s_mov_b32 s13, s38

;     DI bool next(int i, Unit& u) const {
;         const long L = (long)i * G + c; const int nMz = nM * nZ, nwg = nMz * nN; if (L >= nwg) return false;
;         int wgid = (int)L; { const int q = nwg / NXCD, r = nwg % NXCD, xcd = wgid % NXCD, off = wgid / NXCD; wgid = (xcd < r ? xcd * (q + 1) : r * (q + 1) + (xcd - r) * q) + off; }
;         const int nig = WGM * nN, gid = wgid / nig, fm = gid * WGM, gsz = (nMz - fm) < WGM ? (nMz - fm) : WGM;
;         const int pmz = fm + ((wgid % nig) % gsz); u.pn = (wgid % nig) / gsz;
;         const int z = pmz / nM, pm = pmz - z * nM; u.pm = pm; u.z = z;
;         if (bmode == 0) u.b = B + (unsigned)z * sBz + (unsigned)u.pn * 256u * (unsigned)ldb2;
;         else if (bmode == 1) u.b = B + (unsigned)z * sBz + (unsigned)((u.pn >> 4) * 4096 + 4 * (u.pn & 15)) * (unsigned)ldb2;
.LBB0_279:
	s_ashr_i32 s12, s14, 3
	s_add_i32 s12, s36, s12
	s_ashr_i32 s13, s12, 31
	s_lshr_b32 s13, s13, 27
	s_add_i32 s13, s12, s13
	s_ashr_i32 s14, s13, 5
	s_lshl_b32 s14, s14, 3
	s_sub_i32 s15, 8, s14
	s_min_i32 s15, s15, 8
	s_andn2_b32 s13, s13, 31
	s_sub_i32 s12, s12, s13
	s_nop 0
	s_lshr_b32 s36, s12, 3
	s_and_b32 s12, s12, 7
	s_add_i32 s37, s14, s12
	s_lshl_b32 s12, s37, 20
	s_lshl_b32 s13, s36, 18
	s_add_i32 s12, s13, s12
	s_add_i32 s38, s12, 0x32000000
	s_mov_b32 s41, s38

; #define G_STAGE_A(bufoff, p0, p1, koff) do { \
;         __builtin_amdgcn_global_load_lds((const unsigned*)(gbase + (size_t)(unsigned)((p0) + (koff) + voffA[0])), (LAS unsigned*)(lds + (bufoff) + ldsw), 16, 0, 0); \
;         __builtin_amdgcn_global_load_lds((const unsigned*)(gbase + (size_t)(unsigned)((p1) + (koff) + voffA[1])), (LAS unsigned*)(lds + (bufoff) + ldsw + 8192), 16, 0, 0); } while (0)
; #define G_STAGE_B(bufoff, p, koff) do { \
;         __builtin_amdgcn_global_load_lds((const unsigned*)(gbase + (size_t)(unsigned)((p) + (koff) + voffB[0])), (LAS unsigned*)(lds + (bufoff) + ldsw), 16, 0, 0); \
;         __builtin_amdgcn_global_load_lds((const unsigned*)(gbase + (size_t)(unsigned)((p) + (koff) + voffB[1])), (LAS unsigned*)(lds + (bufoff) + ldsw + 8192), 16, 0, 0); } while (0)
; #define G_LDA(dst, b, h) do { _Pragma("unroll") for (int m = 0; m < 4; ++m) _Pragma("unroll") for (int k = 0; k < 2; ++k) dst[m][k] = *(const LAS bf16x8*)(lds + G_SA(b, h) + aoff + m * 2048 + k * 1024); } while (0)
; #define G_LDB(dst, b, h) do { _Pragma("unroll") for (int n = 0; n < 2; ++n) _Pragma("unroll") for (int k = 0; k < 2; ++k) dst[n][k] = *(const LAS bf16x8*)(lds + G_SB(b, h) + boff + n * 2048 + k * 1024); } while (0)
; #define G_WAIT_V(n) asm volatile("s_waitcnt vmcnt(" #n ")" ::: "memory")
; #define G_WAIT_L(n) asm volatile("s_waitcnt lgkmcnt(" #n ")" ::: "memory")
; template <class Epi>
; DI void gemm_phase(LAS unsigned char* lds, const Sched& S, const Epi& E, const int K) {
;     ...
;             const unsigned k1 = (unsigned)(t + 1) * kstepA;
;             const unsigned k2 = last ? 0u : (unsigned)(t + 2) * kstepA, k3 = k2 + kstepA;
;             const unsigned kb2 = last ? 0u : (unsigned)(t + 2) * kstepB, kb3 = kb2 + kstepB;
;             const unsigned x0 = last ? n0 : cur.a0, x1 = last ? n1 : cur.a1, x2 = last ? n2 : cur.a2, x3 = last ? n3 : cur.a3;
;             const unsigned xb = last ? nB : cur.b;
;     ...
;             G_LDB(B0, 0, 0); G_LDB(B1, 0, 1); G_SCHED; G_LDA(At, 0, 0); G_STAGE_A(G_SA(1, 1), cur.a2, cur.a3, k1);
;             G_WAIT_V(8); G_WAIT_L(0); G_BAR; G_MMA(0, 0, At, B0); G_MMA(0, 1, At, B1); G_BAR; G_SCHED;
;             G_LDA(At, 0, 1); G_STAGE_B(G_SB(0, 0), xb, kb2); G_STAGE_B(G_SB(0, 1), xb + hstepB, kb2); G_STAGE_A(G_SA(0, 0), x0, x1, k2);
;             G_WAIT_V(8); G_WAIT_L(0); G_BAR; G_MMA(1, 0, At, B0); G_MMA(1, 1, At, B1); G_BAR; G_SCHED;
.LBB0_281:
	s_add_u32 s14, s12, 0x100
	s_addc_u32 s15, s13, 0
	s_cmp_eq_u32 s44, 4
	s_cselect_b32 s40, 0, s14
	s_cselect_b32 s46, s41, s35
	s_add_i32 s47, 0, 0x10000
	v_add_u32_e32 v132, s47, v136
	s_add_i32 s48, 0, 0x14000
	ds_read_b128 v[144:147], v132
	ds_read_b128 v[148:151], v132 offset:1024
	ds_read_b128 v[152:155], v132 offset:2048
	ds_read_b128 v[156:159], v132 offset:3072
	v_add_u32_e32 v132, s48, v136
	ds_read_b128 v[160:163], v132
	ds_read_b128 v[164:167], v132 offset:1024
	ds_read_b128 v[168:171], v132 offset:2048
	ds_read_b128 v[172:175], v132 offset:3072
	s_or_b32 s45, s40, 0x80
	v_lshl_add_u64 v[132:133], v[130:131], 0, s[12:13]
	s_add_i32 m0, s17, 0xc000
	ds_read_b128 v[176:179], v143
	ds_read_b128 v[180:183], v143 offset:1024
	ds_read_b128 v[194:197], v143 offset:2048
	ds_read_b128 v[198:201], v143 offset:3072
	ds_read_b128 v[202:205], v143 offset:4096
	ds_read_b128 v[206:209], v143 offset:5120
	ds_read_b128 v[210:213], v143 offset:6144
	ds_read_b128 v[214:217], v143 offset:7168
	global_load_lds_dwordx4 v[132:133], off
	v_lshl_add_u64 v[132:133], v[128:129], 0, s[12:13]
	s_add_i32 m0, s17, 0xe000
	s_nop 0
	global_load_lds_dwordx4 v[132:133], off
	s_add_i32 s12, s40, s46
	s_add_i32 s13, s47, s16
	v_add_u32_e32 v132, s12, v134
	s_mov_b32 m0, s13
	s_waitcnt vmcnt(8) lgkmcnt(0)
	s_barrier
	s_setprio 1
	v_mfma_f32_16x16x32_bf16 v[124:127], v[144:147], v[176:179], v[124:127]
	v_mfma_f32_16x16x32_bf16 v[120:123], v[152:155], v[176:179], v[120:123]
	v_mfma_f32_16x16x32_bf16 v[116:119], v[144:147], v[194:197], v[116:119]
	v_mfma_f32_16x16x32_bf16 v[112:115], v[152:155], v[194:197], v[112:115]
	v_mfma_f32_16x16x32_bf16 v[108:111], v[144:147], v[202:205], v[108:111]
	v_mfma_f32_16x16x32_bf16 v[104:107], v[152:155], v[202:205], v[104:107]
	v_mfma_f32_16x16x32_bf16 v[100:103], v[144:147], v[210:213], v[100:103]
	v_mfma_f32_16x16x32_bf16 v[96:99], v[152:155], v[210:213], v[96:99]
	v_mfma_f32_16x16x32_bf16 v[124:127], v[148:151], v[180:183], v[124:127]
	v_mfma_f32_16x16x32_bf16 v[120:123], v[156:159], v[180:183], v[120:123]
	v_mfma_f32_16x16x32_bf16 v[116:119], v[148:151], v[198:201], v[116:119]
	v_mfma_f32_16x16x32_bf16 v[112:115], v[156:159], v[198:201], v[112:115]
	v_mfma_f32_16x16x32_bf16 v[108:111], v[148:151], v[206:209], v[108:111]
	v_mfma_f32_16x16x32_bf16 v[104:107], v[156:159], v[206:209], v[104:107]
	v_mfma_f32_16x16x32_bf16 v[100:103], v[148:151], v[214:217], v[100:103]
	v_mfma_f32_16x16x32_bf16 v[96:99], v[156:159], v[214:217], v[96:99]
	v_mfma_f32_16x16x32_bf16 v[92:95], v[160:163], v[176:179], v[92:95]
	v_mfma_f32_16x16x32_bf16 v[88:91], v[168:171], v[176:179], v[88:91]
	v_mfma_f32_16x16x32_bf16 v[84:87], v[160:163], v[194:197], v[84:87]
	v_mfma_f32_16x16x32_bf16 v[80:83], v[168:171], v[194:197], v[80:83]
	v_mfma_f32_16x16x32_bf16 v[76:79], v[160:163], v[202:205], v[76:79]
	v_mfma_f32_16x16x32_bf16 v[72:75], v[168:171], v[202:205], v[72:75]
	v_mfma_f32_16x16x32_bf16 v[68:71], v[160:163], v[210:213], v[68:71]
	v_mfma_f32_16x16x32_bf16 v[64:67], v[168:171], v[210:213], v[64:67]
	v_mfma_f32_16x16x32_bf16 v[92:95], v[164:167], v[180:183], v[92:95]
	v_mfma_f32_16x16x32_bf16 v[88:91], v[172:175], v[180:183], v[88:91]
	v_mfma_f32_16x16x32_bf16 v[84:87], v[164:167], v[198:201], v[84:87]
	v_mfma_f32_16x16x32_bf16 v[80:83], v[172:175], v[198:201], v[80:83]
	v_mfma_f32_16x16x32_bf16 v[76:79], v[164:167], v[206:209], v[76:79]
	v_mfma_f32_16x16x32_bf16 v[72:75], v[172:175], v[206:209], v[72:75]
	v_mfma_f32_16x16x32_bf16 v[68:71], v[164:167], v[214:217], v[68:71]
	v_mfma_f32_16x16x32_bf16 v[64:67], v[172:175], v[214:217], v[64:67]
	s_setprio 0
	s_barrier
	ds_read_b128 v[176:179], v143 offset:16384
	ds_read_b128 v[180:183], v143 offset:17408
	ds_read_b128 v[194:197], v143 offset:18432
	ds_read_b128 v[198:201], v143 offset:19456
	ds_read_b128 v[202:205], v143 offset:20480
	ds_read_b128 v[206:209], v143 offset:21504
	ds_read_b128 v[210:213], v143 offset:22528
	ds_read_b128 v[214:217], v143 offset:23552
	global_load_lds_dwordx4 v132, s[82:83]
	v_add_u32_e32 v132, s12, v135
	s_add_i32 s12, s46, 0x20000
	s_add_i32 m0, s13, 0x2000
	s_add_i32 s13, s12, s40
	s_add_i32 s47, s48, s16
	global_load_lds_dwordx4 v132, s[82:83]
	v_add_u32_e32 v132, s13, v134
	s_mov_b32 m0, s47
	s_nop 0
	global_load_lds_dwordx4 v132, s[82:83]
	v_add_u32_e32 v132, s13, v135
	s_add_i32 m0, s47, 0x2000
	s_nop 0
	global_load_lds_dwordx4 v132, s[82:83]
	v_add_u32_e32 v132, s40, v141
	s_mov_b32 m0, s17
	s_nop 0
	global_load_lds_dwordx4 v132, s[82:83]
	v_add_u32_e32 v132, s40, v142
	s_mov_b32 m0, s18
	s_nop 0
	global_load_lds_dwordx4 v132, s[82:83]
	s_waitcnt vmcnt(8) lgkmcnt(0)
	s_barrier
; #define G_STAGE_A(bufoff, p0, p1, koff) do { \
;         __builtin_amdgcn_global_load_lds((const unsigned*)(gbase + (size_t)(unsigned)((p0) + (koff) + voffA[0])), (LAS unsigned*)(lds + (bufoff) + ldsw), 16, 0, 0); \
;         __builtin_amdgcn_global_load_lds((const unsigned*)(gbase + (size_t)(unsigned)((p1) + (koff) + voffA[1])), (LAS unsigned*)(lds + (bufoff) + ldsw + 8192), 16, 0, 0); } while (0)
; #define G_STAGE_B(bufoff, p, koff) do { \
;         __builtin_amdgcn_global_load_lds((const unsigned*)(gbase + (size_t)(unsigned)((p) + (koff) + voffB[0])), (LAS unsigned*)(lds + (bufoff) + ldsw), 16, 0, 0); \
;         __builtin_amdgcn_global_load_lds((const unsigned*)(gbase + (size_t)(unsigned)((p) + (koff) + voffB[1])), (LAS unsigned*)(lds + (bufoff) + ldsw + 8192), 16, 0, 0); } while (0)
; #define G_LDA(dst, b, h) do { _Pragma("unroll") for (int m = 0; m < 4; ++m) _Pragma("unroll") for (int k = 0; k < 2; ++k) dst[m][k] = *(const LAS bf16x8*)(lds + G_SA(b, h) + aoff + m * 2048 + k * 1024); } while (0)
; #define G_LDB(dst, b, h) do { _Pragma("unroll") for (int n = 0; n < 2; ++n) _Pragma("unroll") for (int k = 0; k < 2; ++k) dst[n][k] = *(const LAS bf16x8*)(lds + G_SB(b, h) + boff + n * 2048 + k * 1024); } while (0)
; #define G_MMA(ai, bj, At, Bt) do { __builtin_amdgcn_s_setprio(1); _Pragma("unroll") for (int m = 0; m < 4; ++m) _Pragma("unroll") for (int n = 0; n < 2; ++n) _Pragma("unroll") for (int k = 0; k < 2; ++k) \
;         acc[ai][bj][m][n] = __builtin_amdgcn_mfma_f32_16x16x32_bf16(Bt[n][k], At[m][k], acc[ai][bj][m][n], 0, 0, 0); __builtin_amdgcn_s_setprio(0); } while (0)
; template <class Epi>
; DI void gemm_phase(LAS unsigned char* lds, const Sched& S, const Epi& E, const int K) {
;     ...
;             G_LDB(B0, 0, 0); G_LDB(B1, 0, 1); G_SCHED; G_LDA(At, 0, 0); G_STAGE_A(G_SA(1, 1), cur.a2, cur.a3, k1);
;             G_WAIT_V(8); G_WAIT_L(0); G_BAR; G_MMA(0, 0, At, B0); G_MMA(0, 1, At, B1); G_BAR; G_SCHED;
;             G_LDA(At, 0, 1); G_STAGE_B(G_SB(0, 0), xb, kb2); G_STAGE_B(G_SB(0, 1), xb + hstepB, kb2); G_STAGE_A(G_SA(0, 0), x0, x1, k2);
;             G_WAIT_V(8); G_WAIT_L(0); G_BAR; G_MMA(1, 0, At, B0); G_MMA(1, 1, At, B1); G_BAR; G_SCHED;
;             G_LDB(B0, 1, 0); G_LDB(B1, 1, 1); G_SCHED; G_LDA(At, 1, 0); G_STAGE_A(G_SA(0, 1), x2, x3, k2);
;             G_WAIT_V(8); G_WAIT_L(0); G_BAR; G_MMA(0, 0, At, B0); G_MMA(0, 1, At, B1); G_BAR; G_SCHED;
	s_setprio 1
	v_mfma_f32_16x16x32_bf16 v[60:63], v[144:147], v[176:179], v[60:63]
	v_mfma_f32_16x16x32_bf16 v[56:59], v[152:155], v[176:179], v[56:59]
	v_mfma_f32_16x16x32_bf16 v[52:55], v[144:147], v[194:197], v[52:55]
	v_mfma_f32_16x16x32_bf16 v[48:51], v[152:155], v[194:197], v[48:51]
	v_mfma_f32_16x16x32_bf16 v[44:47], v[144:147], v[202:205], v[44:47]
	v_mfma_f32_16x16x32_bf16 v[40:43], v[152:155], v[202:205], v[40:43]
	v_mfma_f32_16x16x32_bf16 v[36:39], v[144:147], v[210:213], v[36:39]
	v_mfma_f32_16x16x32_bf16 v[32:35], v[152:155], v[210:213], v[32:35]
	v_mfma_f32_16x16x32_bf16 v[60:63], v[148:151], v[180:183], v[60:63]
	v_mfma_f32_16x16x32_bf16 v[56:59], v[156:159], v[180:183], v[56:59]
	v_mfma_f32_16x16x32_bf16 v[52:55], v[148:151], v[198:201], v[52:55]
	v_mfma_f32_16x16x32_bf16 v[48:51], v[156:159], v[198:201], v[48:51]
	v_mfma_f32_16x16x32_bf16 v[44:47], v[148:151], v[206:209], v[44:47]
	v_mfma_f32_16x16x32_bf16 v[40:43], v[156:159], v[206:209], v[40:43]
	v_mfma_f32_16x16x32_bf16 v[36:39], v[148:151], v[214:217], v[36:39]
	v_mfma_f32_16x16x32_bf16 v[32:35], v[156:159], v[214:217], v[32:35]
	v_mfma_f32_16x16x32_bf16 v[28:31], v[160:163], v[176:179], v[28:31]
	v_mfma_f32_16x16x32_bf16 v[24:27], v[168:171], v[176:179], v[24:27]
	v_mfma_f32_16x16x32_bf16 v[20:23], v[160:163], v[194:197], v[20:23]
	v_mfma_f32_16x16x32_bf16 v[16:19], v[168:171], v[194:197], v[16:19]
	v_mfma_f32_16x16x32_bf16 v[12:15], v[160:163], v[202:205], v[12:15]
	v_mfma_f32_16x16x32_bf16 v[8:11], v[168:171], v[202:205], v[8:11]
	v_mfma_f32_16x16x32_bf16 v[4:7], v[160:163], v[210:213], v[4:7]
	v_mfma_f32_16x16x32_bf16 v[0:3], v[168:171], v[210:213], v[0:3]
	v_mfma_f32_16x16x32_bf16 v[28:31], v[164:167], v[180:183], v[28:31]
	v_mfma_f32_16x16x32_bf16 v[24:27], v[172:175], v[180:183], v[24:27]
	v_mfma_f32_16x16x32_bf16 v[20:23], v[164:167], v[198:201], v[20:23]
	v_mfma_f32_16x16x32_bf16 v[16:19], v[172:175], v[198:201], v[16:19]
	v_mfma_f32_16x16x32_bf16 v[12:15], v[164:167], v[206:209], v[12:15]
	v_mfma_f32_16x16x32_bf16 v[8:11], v[172:175], v[206:209], v[8:11]
	v_mfma_f32_16x16x32_bf16 v[4:7], v[164:167], v[214:217], v[4:7]
	v_mfma_f32_16x16x32_bf16 v[0:3], v[172:175], v[214:217], v[0:3]
	s_setprio 0
	s_barrier
	s_add_i32 s13, 0, 0x18000
	v_add_u32_e32 v132, s13, v136
	s_add_i32 s47, 0, 0x1c000
	ds_read_b128 v[144:147], v132
	ds_read_b128 v[148:151], v132 offset:1024
	ds_read_b128 v[152:155], v132 offset:2048
	ds_read_b128 v[156:159], v132 offset:3072
	v_add_u32_e32 v132, s47, v136
	ds_read_b128 v[160:163], v132
	ds_read_b128 v[164:167], v132 offset:1024
	ds_read_b128 v[168:171], v132 offset:2048
	ds_read_b128 v[172:175], v132 offset:3072
	s_mov_b32 m0, s19
	v_add_u32_e32 v132, s40, v139
	ds_read_b128 v[176:179], v143 offset:32768
	ds_read_b128 v[180:183], v143 offset:33792
	ds_read_b128 v[194:197], v143 offset:34816
	ds_read_b128 v[198:201], v143 offset:35840
	ds_read_b128 v[202:205], v143 offset:36864
	ds_read_b128 v[206:209], v143 offset:37888
	ds_read_b128 v[210:213], v143 offset:38912
	ds_read_b128 v[214:217], v143 offset:39936
	global_load_lds_dwordx4 v132, s[82:83]
	v_add_u32_e32 v132, s40, v140
	s_mov_b32 m0, s20
	s_nop 0
	global_load_lds_dwordx4 v132, s[82:83]
	s_add_i32 s40, s45, s46
	s_add_i32 s13, s13, s16
	v_add_u32_e32 v132, s40, v134
	s_mov_b32 m0, s13
	s_waitcnt vmcnt(8) lgkmcnt(0)
	s_barrier
	s_setprio 1
	v_mfma_f32_16x16x32_bf16 v[124:127], v[144:147], v[176:179], v[124:127]
	v_mfma_f32_16x16x32_bf16 v[120:123], v[152:155], v[176:179], v[120:123]
	v_mfma_f32_16x16x32_bf16 v[116:119], v[144:147], v[194:197], v[116:119]
	v_mfma_f32_16x16x32_bf16 v[112:115], v[152:155], v[194:197], v[112:115]
	v_mfma_f32_16x16x32_bf16 v[108:111], v[144:147], v[202:205], v[108:111]
	v_mfma_f32_16x16x32_bf16 v[104:107], v[152:155], v[202:205], v[104:107]
	v_mfma_f32_16x16x32_bf16 v[100:103], v[144:147], v[210:213], v[100:103]
	v_mfma_f32_16x16x32_bf16 v[96:99], v[152:155], v[210:213], v[96:99]
	v_mfma_f32_16x16x32_bf16 v[124:127], v[148:151], v[180:183], v[124:127]
	v_mfma_f32_16x16x32_bf16 v[120:123], v[156:159], v[180:183], v[120:123]
	v_mfma_f32_16x16x32_bf16 v[116:119], v[148:151], v[198:201], v[116:119]
	v_mfma_f32_16x16x32_bf16 v[112:115], v[156:159], v[198:201], v[112:115]
	v_mfma_f32_16x16x32_bf16 v[108:111], v[148:151], v[206:209], v[108:111]
	v_mfma_f32_16x16x32_bf16 v[104:107], v[156:159], v[206:209], v[104:107]
	v_mfma_f32_16x16x32_bf16 v[100:103], v[148:151], v[214:217], v[100:103]
	v_mfma_f32_16x16x32_bf16 v[96:99], v[156:159], v[214:217], v[96:99]
	v_mfma_f32_16x16x32_bf16 v[92:95], v[160:163], v[176:179], v[92:95]
	v_mfma_f32_16x16x32_bf16 v[88:91], v[168:171], v[176:179], v[88:91]
	v_mfma_f32_16x16x32_bf16 v[84:87], v[160:163], v[194:197], v[84:87]
	v_mfma_f32_16x16x32_bf16 v[80:83], v[168:171], v[194:197], v[80:83]
	v_mfma_f32_16x16x32_bf16 v[76:79], v[160:163], v[202:205], v[76:79]
	v_mfma_f32_16x16x32_bf16 v[72:75], v[168:171], v[202:205], v[72:75]
	v_mfma_f32_16x16x32_bf16 v[68:71], v[160:163], v[210:213], v[68:71]
	v_mfma_f32_16x16x32_bf16 v[64:67], v[168:171], v[210:213], v[64:67]
	v_mfma_f32_16x16x32_bf16 v[92:95], v[164:167], v[180:183], v[92:95]
	v_mfma_f32_16x16x32_bf16 v[88:91], v[172:175], v[180:183], v[88:91]
	v_mfma_f32_16x16x32_bf16 v[84:87], v[164:167], v[198:201], v[84:87]
	v_mfma_f32_16x16x32_bf16 v[80:83], v[172:175], v[198:201], v[80:83]
	v_mfma_f32_16x16x32_bf16 v[76:79], v[164:167], v[206:209], v[76:79]
	v_mfma_f32_16x16x32_bf16 v[72:75], v[172:175], v[206:209], v[72:75]
	v_mfma_f32_16x16x32_bf16 v[68:71], v[164:167], v[214:217], v[68:71]
	v_mfma_f32_16x16x32_bf16 v[64:67], v[172:175], v[214:217], v[64:67]
	s_setprio 0
	s_barrier
; #define G_STAGE_A(bufoff, p0, p1, koff) do { \
;         __builtin_amdgcn_global_load_lds((const unsigned*)(gbase + (size_t)(unsigned)((p0) + (koff) + voffA[0])), (LAS unsigned*)(lds + (bufoff) + ldsw), 16, 0, 0); \
;         __builtin_amdgcn_global_load_lds((const unsigned*)(gbase + (size_t)(unsigned)((p1) + (koff) + voffA[1])), (LAS unsigned*)(lds + (bufoff) + ldsw + 8192), 16, 0, 0); } while (0)
; #define G_STAGE_B(bufoff, p, koff) do { \
;         __builtin_amdgcn_global_load_lds((const unsigned*)(gbase + (size_t)(unsigned)((p) + (koff) + voffB[0])), (LAS unsigned*)(lds + (bufoff) + ldsw), 16, 0, 0); \
;         __builtin_amdgcn_global_load_lds((const unsigned*)(gbase + (size_t)(unsigned)((p) + (koff) + voffB[1])), (LAS unsigned*)(lds + (bufoff) + ldsw + 8192), 16, 0, 0); } while (0)
; #define G_LDA(dst, b, h) do { _Pragma("unroll") for (int m = 0; m < 4; ++m) _Pragma("unroll") for (int k = 0; k < 2; ++k) dst[m][k] = *(const LAS bf16x8*)(lds + G_SA(b, h) + aoff + m * 2048 + k * 1024); } while (0)
; #define G_MMA(ai, bj, At, Bt) do { __builtin_amdgcn_s_setprio(1); _Pragma("unroll") for (int m = 0; m < 4; ++m) _Pragma("unroll") for (int n = 0; n < 2; ++n) _Pragma("unroll") for (int k = 0; k < 2; ++k) \
;         acc[ai][bj][m][n] = __builtin_amdgcn_mfma_f32_16x16x32_bf16(Bt[n][k], At[m][k], acc[ai][bj][m][n], 0, 0, 0); __builtin_amdgcn_s_setprio(0); } while (0)
; #define G_WAIT_V(n) asm volatile("s_waitcnt vmcnt(" #n ")" ::: "memory")
; #define G_WAIT_L(n) asm volatile("s_waitcnt lgkmcnt(" #n ")" ::: "memory")
; #define G_BAR __builtin_amdgcn_s_barrier()
; #define G_SCHED __builtin_amdgcn_sched_barrier(0)
; template <class Epi>
; DI void gemm_phase(LAS unsigned char* lds, const Sched& S, const Epi& E, const int K) {
;     ...
;             G_LDA(At, 1, 1); G_STAGE_B(G_SB(1, 0), xb, kb3); G_STAGE_B(G_SB(1, 1), xb + hstepB, kb3); G_STAGE_A(G_SA(1, 0), x0, x1, k3);
;             G_WAIT_V(8); G_WAIT_L(0); G_BAR; G_MMA(1, 0, At, B0); G_MMA(1, 1, At, B1); G_BAR; G_SCHED;
;     ...
;         if (wr == 0) G_BAR;
	ds_read_b128 v[176:179], v143 offset:49152
	ds_read_b128 v[180:183], v143 offset:50176
	ds_read_b128 v[194:197], v143 offset:51200
	ds_read_b128 v[198:201], v143 offset:52224
	ds_read_b128 v[202:205], v143 offset:53248
	ds_read_b128 v[206:209], v143 offset:54272
	ds_read_b128 v[210:213], v143 offset:55296
	ds_read_b128 v[214:217], v143 offset:56320
	global_load_lds_dwordx4 v132, s[82:83]
	v_add_u32_e32 v132, s40, v135
	s_add_i32 m0, s13, 0x2000
	s_add_i32 s12, s45, s12
	s_add_i32 s13, s47, s16
	global_load_lds_dwordx4 v132, s[82:83]
	v_add_u32_e32 v132, s12, v134
	s_mov_b32 m0, s13
	s_nop 0
	global_load_lds_dwordx4 v132, s[82:83]
	v_add_u32_e32 v132, s12, v135
	s_add_i32 m0, s13, 0x2000
	s_nop 0
	global_load_lds_dwordx4 v132, s[82:83]
	v_add_u32_e32 v132, s45, v141
	s_mov_b32 m0, s21
	s_nop 0
	global_load_lds_dwordx4 v132, s[82:83]
	v_add_u32_e32 v132, s45, v142
	s_mov_b32 m0, s24
	s_nop 0
	global_load_lds_dwordx4 v132, s[82:83]
	s_waitcnt vmcnt(8) lgkmcnt(0)
	s_barrier
	s_setprio 1
	v_mfma_f32_16x16x32_bf16 v[60:63], v[144:147], v[176:179], v[60:63]
	v_mfma_f32_16x16x32_bf16 v[56:59], v[152:155], v[176:179], v[56:59]
	v_mfma_f32_16x16x32_bf16 v[52:55], v[144:147], v[194:197], v[52:55]
	v_mfma_f32_16x16x32_bf16 v[48:51], v[152:155], v[194:197], v[48:51]
	v_mfma_f32_16x16x32_bf16 v[44:47], v[144:147], v[202:205], v[44:47]
	v_mfma_f32_16x16x32_bf16 v[40:43], v[152:155], v[202:205], v[40:43]
	v_mfma_f32_16x16x32_bf16 v[36:39], v[144:147], v[210:213], v[36:39]
	v_mfma_f32_16x16x32_bf16 v[32:35], v[152:155], v[210:213], v[32:35]
	v_mfma_f32_16x16x32_bf16 v[60:63], v[148:151], v[180:183], v[60:63]
	v_mfma_f32_16x16x32_bf16 v[56:59], v[156:159], v[180:183], v[56:59]
	v_mfma_f32_16x16x32_bf16 v[52:55], v[148:151], v[198:201], v[52:55]
	v_mfma_f32_16x16x32_bf16 v[48:51], v[156:159], v[198:201], v[48:51]
	v_mfma_f32_16x16x32_bf16 v[44:47], v[148:151], v[206:209], v[44:47]
	v_mfma_f32_16x16x32_bf16 v[40:43], v[156:159], v[206:209], v[40:43]
	v_mfma_f32_16x16x32_bf16 v[36:39], v[148:151], v[214:217], v[36:39]
	v_mfma_f32_16x16x32_bf16 v[32:35], v[156:159], v[214:217], v[32:35]
	v_mfma_f32_16x16x32_bf16 v[28:31], v[160:163], v[176:179], v[28:31]
	v_mfma_f32_16x16x32_bf16 v[24:27], v[168:171], v[176:179], v[24:27]
	v_mfma_f32_16x16x32_bf16 v[20:23], v[160:163], v[194:197], v[20:23]
	v_mfma_f32_16x16x32_bf16 v[16:19], v[168:171], v[194:197], v[16:19]
	v_mfma_f32_16x16x32_bf16 v[12:15], v[160:163], v[202:205], v[12:15]
	v_mfma_f32_16x16x32_bf16 v[8:11], v[168:171], v[202:205], v[8:11]
	v_mfma_f32_16x16x32_bf16 v[4:7], v[160:163], v[210:213], v[4:7]
	v_mfma_f32_16x16x32_bf16 v[0:3], v[168:171], v[210:213], v[0:3]
	v_mfma_f32_16x16x32_bf16 v[28:31], v[164:167], v[180:183], v[28:31]
	v_mfma_f32_16x16x32_bf16 v[24:27], v[172:175], v[180:183], v[24:27]
	v_mfma_f32_16x16x32_bf16 v[20:23], v[164:167], v[198:201], v[20:23]
	v_mfma_f32_16x16x32_bf16 v[16:19], v[172:175], v[198:201], v[16:19]
	v_mfma_f32_16x16x32_bf16 v[12:15], v[164:167], v[206:209], v[12:15]
	v_mfma_f32_16x16x32_bf16 v[8:11], v[172:175], v[206:209], v[8:11]
	v_mfma_f32_16x16x32_bf16 v[4:7], v[164:167], v[214:217], v[4:7]
	v_mfma_f32_16x16x32_bf16 v[0:3], v[172:175], v[214:217], v[0:3]
	s_setprio 0
	s_barrier
	s_add_i32 s44, s44, 2
	s_cmp_gt_u32 s44, 5
	s_mov_b64 s[12:13], s[14:15]
	s_cbranch_scc0 .LBB0_281
	s_and_b64 vcc, exec, s[6:7]
	s_cbranch_vccz .LBB0_284
	s_barrier

;     DI bool next(int i, Unit& u) const {
;         const long L = (long)i * G + c; const int nMz = nM * nZ, nwg = nMz * nN; if (L >= nwg) return false;
;         int wgid = (int)L; { const int q = nwg / NXCD, r = nwg % NXCD, xcd = wgid % NXCD, off = wgid / NXCD; wgid = (xcd < r ? xcd * (q + 1) : r * (q + 1) + (xcd - r) * q) + off; }
;         const int nig = WGM * nN, gid = wgid / nig, fm = gid * WGM, gsz = (nMz - fm) < WGM ? (nMz - fm) : WGM;
;         const int pmz = fm + ((wgid % nig) % gsz); u.pn = (wgid % nig) / gsz;
;         const int z = pmz / nM, pm = pmz - z * nM; u.pm = pm; u.z = z;
;         if (bmode == 0) u.b = B + (unsigned)z * sBz + (unsigned)u.pn * 256u * (unsigned)ldb2;
;         else if (bmode == 1) u.b = B + (unsigned)z * sBz + (unsigned)((u.pn >> 4) * 4096 + 4 * (u.pn & 15)) * (unsigned)ldb2;
;         else u.b = B + (unsigned)z * sBz + (unsigned)u.pn * 4u * 16384u;
;         if (mode == 0) { const unsigned a = A + (unsigned)z * sAz + (unsigned)pm * 256u * (unsigned)lda2; u.a0 = a; u.a1 = a + 64u * lda2; u.a2 = a + 128u * lda2; u.a3 = a + 192u * lda2; }
;         else if (mode == 1) { const int g = pm * 256; u.a0 = A + (unsigned)hpad_row(g) * lda2; u.a1 = A + (unsigned)hpad_row(g + 64) * lda2; u.a2 = A + (unsigned)hpad_row(g + 128) * lda2; u.a3 = A + (unsigned)hpad_row(g + 192) * lda2; }
.LBB0_491:
	s_add_i32 s71, s61, 1
	s_mul_i32 s7, s71, s3
	s_mul_hi_i32 s6, s71, s3
	s_add_u32 s10, s7, s2
	s_addc_u32 s11, s6, s77
	v_mov_b64_e32 v[128:129], 0x880
	v_cmp_lt_i64_e64 s[8:9], s[10:11], v[128:129]
	v_mov_b64_e32 v[128:129], 0x87f
	v_cmp_gt_i64_e64 s[6:7], s[10:11], v[128:129]
	s_and_b64 vcc, exec, s[6:7]
	s_mov_b32 s11, s46
	s_mov_b32 s20, s45
	s_mov_b32 s21, s44
	s_mov_b32 s24, s41
	s_mov_b32 s25, s40
	s_cbranch_vccnz .LBB0_510
	s_ashr_i32 s11, s10, 31
	s_lshr_b32 s11, s11, 29
	s_add_i32 s11, s10, s11
	s_ashr_i32 s20, s11, 3
	s_and_b32 s11, s11, -8
	s_sub_i32 s10, s10, s11
	s_cmp_lt_i32 s10, 0
	s_cselect_b32 s11, s81, 0x110
	s_mul_i32 s10, s10, s11
	s_add_i32 s10, s10, s20
	s_ashr_i32 s11, s10, 31
	s_lshr_b32 s11, s11, 25
	s_add_i32 s11, s10, s11
	s_ashr_i32 s20, s11, 7
	s_lshl_b32 s20, s20, 3
	s_sub_i32 s21, 0x88, s20
	s_min_i32 s21, s21, 8
	s_and_b32 s11, s11, 0xffffff80
	s_sub_i32 s10, s10, s11
	s_nop 0
	s_lshr_b32 s62, s10, 3
	s_and_b32 s10, s10, 7
	s_add_i32 s20, s20, s10
	s_mul_hi_i32 s10, s20, 0x78787879
	s_lshr_b32 s11, s10, 31
	s_ashr_i32 s10, s10, 6
	s_add_i32 s10, s10, s11
	s_mulk_i32 s10, 0x88
	s_sub_i32 s63, s20, s10
	s_lshl_b32 s20, s63, 8
	s_cmpk_gt_i32 s63, 0x7f
	s_mov_b64 s[10:11], -1
	s_cbranch_scc0 .LBB0_494
	s_add_i32 s10, s20, 0xffff8000
	s_lshr_b32 s10, s10, 8
	s_mul_i32 s21, s10, 0x102
	s_mov_b64 s[10:11], 0

; #define G_STAGE_A(bufoff, p0, p1, koff) do { \
;         __builtin_amdgcn_global_load_lds((const unsigned*)(gbase + (size_t)(unsigned)((p0) + (koff) + voffA[0])), (LAS unsigned*)(lds + (bufoff) + ldsw), 16, 0, 0); \
;         __builtin_amdgcn_global_load_lds((const unsigned*)(gbase + (size_t)(unsigned)((p1) + (koff) + voffA[1])), (LAS unsigned*)(lds + (bufoff) + ldsw + 8192), 16, 0, 0); } while (0)
; #define G_STAGE_B(bufoff, p, koff) do { \
;         __builtin_amdgcn_global_load_lds((const unsigned*)(gbase + (size_t)(unsigned)((p) + (koff) + voffB[0])), (LAS unsigned*)(lds + (bufoff) + ldsw), 16, 0, 0); \
;         __builtin_amdgcn_global_load_lds((const unsigned*)(gbase + (size_t)(unsigned)((p) + (koff) + voffB[1])), (LAS unsigned*)(lds + (bufoff) + ldsw + 8192), 16, 0, 0); } while (0)
; #define G_LDA(dst, b, h) do { _Pragma("unroll") for (int m = 0; m < 4; ++m) _Pragma("unroll") for (int k = 0; k < 2; ++k) dst[m][k] = *(const LAS bf16x8*)(lds + G_SA(b, h) + aoff + m * 2048 + k * 1024); } while (0)
; #define G_LDB(dst, b, h) do { _Pragma("unroll") for (int n = 0; n < 2; ++n) _Pragma("unroll") for (int k = 0; k < 2; ++k) dst[n][k] = *(const LAS bf16x8*)(lds + G_SB(b, h) + boff + n * 2048 + k * 1024); } while (0)
; #define G_WAIT_V(n) asm volatile("s_waitcnt vmcnt(" #n ")" ::: "memory")
; template <class Epi>
; DI void gemm_phase(LAS unsigned char* lds, const Sched& S, const Epi& E, const int K) {
;     ...
;             const bool last = (t == nt - 2);
;             const unsigned k1 = (unsigned)(t + 1) * kstepA;
;             const unsigned k2 = last ? 0u : (unsigned)(t + 2) * kstepA, k3 = k2 + kstepA;
;             const unsigned kb2 = last ? 0u : (unsigned)(t + 2) * kstepB, kb3 = kb2 + kstepB;
;             const unsigned x0 = last ? n0 : cur.a0, x1 = last ? n1 : cur.a1, x2 = last ? n2 : cur.a2, x3 = last ? n3 : cur.a3;
;             const unsigned xb = last ? nB : cur.b;
;     ...
;             G_LDB(B0, 0, 0); G_LDB(B1, 0, 1); G_SCHED; G_LDA(At, 0, 0); G_STAGE_A(G_SA(1, 1), cur.a2, cur.a3, k1);
;             G_WAIT_V(8); G_WAIT_L(0); G_BAR; G_MMA(0, 0, At, B0); G_MMA(0, 1, At, B1); G_BAR; G_SCHED;
;             G_LDA(At, 0, 1); G_STAGE_B(G_SB(0, 0), xb, kb2); G_STAGE_B(G_SB(0, 1), xb + hstepB, kb2); G_STAGE_A(G_SA(0, 0), x0, x1, k2);
;             G_WAIT_V(8); G_WAIT_L(0); G_BAR; G_MMA(1, 0, At, B0); G_MMA(1, 1, At, B1); G_BAR; G_SCHED;
.LBB0_511:
	s_add_i32 s27, s26, 0x100
	s_cmp_eq_u32 s10, 28
	s_cselect_b32 s48, 0, s27
	s_cselect_b32 s72, s20, s45
	s_cselect_b32 s73, s24, s41
	s_cselect_b32 s75, s21, s44
	s_cselect_b32 s78, s11, s46
	s_cselect_b32 s37, s25, s40
	s_add_i32 s79, 0, 0x10000
	v_add_u32_e32 v130, s79, v148
	s_add_i32 s80, 0, 0x14000
	ds_read_b128 v[138:141], v130
	ds_read_b128 v[154:157], v130 offset:1024
	ds_read_b128 v[158:161], v130 offset:2048
	ds_read_b128 v[162:165], v130 offset:3072
	v_add_u32_e32 v130, s80, v148
	ds_read_b128 v[166:169], v130
	ds_read_b128 v[170:173], v130 offset:1024
	ds_read_b128 v[174:177], v130 offset:2048
	ds_read_b128 v[178:181], v130 offset:3072
	s_or_b32 s36, s48, 0x80
	v_add_u32_e32 v130, s26, v129
	s_add_i32 m0, s50, 0xc000
	ds_read_b128 v[194:197], v152
	ds_read_b128 v[198:201], v152 offset:1024
	ds_read_b128 v[202:205], v152 offset:2048
	ds_read_b128 v[206:209], v152 offset:3072
	ds_read_b128 v[210:213], v152 offset:4096
	ds_read_b128 v[214:217], v152 offset:5120
	ds_read_b128 v[218:221], v152 offset:6144
	ds_read_b128 v[222:225], v152 offset:7168
	global_load_lds_dwordx4 v130, s[82:83]
	v_add_u32_e32 v130, s26, v128
	s_add_i32 m0, s50, 0xe000
	s_nop 0
	global_load_lds_dwordx4 v130, s[82:83]
	s_add_i32 s26, s48, s37
	s_add_i32 s79, s79, s47
	v_add_u32_e32 v130, s26, v144
	s_mov_b32 m0, s79
	s_waitcnt vmcnt(8) lgkmcnt(0)
	s_barrier
	s_setprio 1
	v_mfma_f32_16x16x32_bf16 v[124:127], v[138:141], v[194:197], v[124:127]
	v_mfma_f32_16x16x32_bf16 v[120:123], v[158:161], v[194:197], v[120:123]
	v_mfma_f32_16x16x32_bf16 v[116:119], v[138:141], v[202:205], v[116:119]
	v_mfma_f32_16x16x32_bf16 v[112:115], v[158:161], v[202:205], v[112:115]
	v_mfma_f32_16x16x32_bf16 v[108:111], v[138:141], v[210:213], v[108:111]
	v_mfma_f32_16x16x32_bf16 v[104:107], v[158:161], v[210:213], v[104:107]
	v_mfma_f32_16x16x32_bf16 v[100:103], v[138:141], v[218:221], v[100:103]
	v_mfma_f32_16x16x32_bf16 v[96:99], v[158:161], v[218:221], v[96:99]
	v_mfma_f32_16x16x32_bf16 v[124:127], v[154:157], v[198:201], v[124:127]
	v_mfma_f32_16x16x32_bf16 v[120:123], v[162:165], v[198:201], v[120:123]
	v_mfma_f32_16x16x32_bf16 v[116:119], v[154:157], v[206:209], v[116:119]
	v_mfma_f32_16x16x32_bf16 v[112:115], v[162:165], v[206:209], v[112:115]
	v_mfma_f32_16x16x32_bf16 v[108:111], v[154:157], v[214:217], v[108:111]
	v_mfma_f32_16x16x32_bf16 v[104:107], v[162:165], v[214:217], v[104:107]
	v_mfma_f32_16x16x32_bf16 v[100:103], v[154:157], v[222:225], v[100:103]
	v_mfma_f32_16x16x32_bf16 v[96:99], v[162:165], v[222:225], v[96:99]
	v_mfma_f32_16x16x32_bf16 v[92:95], v[166:169], v[194:197], v[92:95]
	v_mfma_f32_16x16x32_bf16 v[88:91], v[174:177], v[194:197], v[88:91]
	v_mfma_f32_16x16x32_bf16 v[84:87], v[166:169], v[202:205], v[84:87]
	v_mfma_f32_16x16x32_bf16 v[80:83], v[174:177], v[202:205], v[80:83]
	v_mfma_f32_16x16x32_bf16 v[76:79], v[166:169], v[210:213], v[76:79]
	v_mfma_f32_16x16x32_bf16 v[72:75], v[174:177], v[210:213], v[72:75]
	v_mfma_f32_16x16x32_bf16 v[68:71], v[166:169], v[218:221], v[68:71]
	v_mfma_f32_16x16x32_bf16 v[64:67], v[174:177], v[218:221], v[64:67]
	v_mfma_f32_16x16x32_bf16 v[92:95], v[170:173], v[198:201], v[92:95]
	v_mfma_f32_16x16x32_bf16 v[88:91], v[178:181], v[198:201], v[88:91]
	v_mfma_f32_16x16x32_bf16 v[84:87], v[170:173], v[206:209], v[84:87]
	v_mfma_f32_16x16x32_bf16 v[80:83], v[178:181], v[206:209], v[80:83]
	v_mfma_f32_16x16x32_bf16 v[76:79], v[170:173], v[214:217], v[76:79]
	v_mfma_f32_16x16x32_bf16 v[72:75], v[178:181], v[214:217], v[72:75]
	v_mfma_f32_16x16x32_bf16 v[68:71], v[170:173], v[222:225], v[68:71]
	v_mfma_f32_16x16x32_bf16 v[64:67], v[178:181], v[222:225], v[64:67]
	s_setprio 0
	s_barrier
	ds_read_b128 v[194:197], v152 offset:16384
	ds_read_b128 v[198:201], v152 offset:17408
	ds_read_b128 v[202:205], v152 offset:18432
	ds_read_b128 v[206:209], v152 offset:19456
	ds_read_b128 v[210:213], v152 offset:20480
	ds_read_b128 v[214:217], v152 offset:21504
	ds_read_b128 v[218:221], v152 offset:22528
	ds_read_b128 v[222:225], v152 offset:23552
	global_load_lds_dwordx4 v130, s[82:83]
	v_add_u32_e32 v130, s26, v146
	s_add_i32 s26, s37, 0x80000
	s_add_i32 m0, s79, 0x2000
	s_add_i32 s79, s26, s48
	s_add_i32 s80, s80, s47
	global_load_lds_dwordx4 v130, s[82:83]
	v_add_u32_e32 v130, s79, v144
	s_mov_b32 m0, s80
	s_nop 0
	global_load_lds_dwordx4 v130, s[82:83]
	v_add_u32_e32 v130, s79, v146
	s_add_i32 m0, s80, 0x2000
	s_nop 0
	global_load_lds_dwordx4 v130, s[82:83]
	v_add_u32_e32 v130, s78, v133
	v_add_u32_e32 v131, s48, v130
	s_mov_b32 m0, s50
	s_nop 0
	global_load_lds_dwordx4 v131, s[82:83]
	v_add_u32_e32 v131, s72, v145
	v_add_u32_e32 v142, s48, v131
	s_mov_b32 m0, s54
	s_nop 0
	global_load_lds_dwordx4 v142, s[82:83]
	s_waitcnt vmcnt(8) lgkmcnt(0)
	s_barrier
; #define G_STAGE_A(bufoff, p0, p1, koff) do { \
;         __builtin_amdgcn_global_load_lds((const unsigned*)(gbase + (size_t)(unsigned)((p0) + (koff) + voffA[0])), (LAS unsigned*)(lds + (bufoff) + ldsw), 16, 0, 0); \
;         __builtin_amdgcn_global_load_lds((const unsigned*)(gbase + (size_t)(unsigned)((p1) + (koff) + voffA[1])), (LAS unsigned*)(lds + (bufoff) + ldsw + 8192), 16, 0, 0); } while (0)
; #define G_LDA(dst, b, h) do { _Pragma("unroll") for (int m = 0; m < 4; ++m) _Pragma("unroll") for (int k = 0; k < 2; ++k) dst[m][k] = *(const LAS bf16x8*)(lds + G_SA(b, h) + aoff + m * 2048 + k * 1024); } while (0)
; #define G_LDB(dst, b, h) do { _Pragma("unroll") for (int n = 0; n < 2; ++n) _Pragma("unroll") for (int k = 0; k < 2; ++k) dst[n][k] = *(const LAS bf16x8*)(lds + G_SB(b, h) + boff + n * 2048 + k * 1024); } while (0)
; #define G_MMA(ai, bj, At, Bt) do { __builtin_amdgcn_s_setprio(1); _Pragma("unroll") for (int m = 0; m < 4; ++m) _Pragma("unroll") for (int n = 0; n < 2; ++n) _Pragma("unroll") for (int k = 0; k < 2; ++k) \
;         acc[ai][bj][m][n] = __builtin_amdgcn_mfma_f32_16x16x32_bf16(Bt[n][k], At[m][k], acc[ai][bj][m][n], 0, 0, 0); __builtin_amdgcn_s_setprio(0); } while (0)
; #define G_WAIT_V(n) asm volatile("s_waitcnt vmcnt(" #n ")" ::: "memory")
; #define G_WAIT_L(n) asm volatile("s_waitcnt lgkmcnt(" #n ")" ::: "memory")
; #define G_BAR __builtin_amdgcn_s_barrier()
; #define G_SCHED __builtin_amdgcn_sched_barrier(0)
; template <class Epi>
; DI void gemm_phase(LAS unsigned char* lds, const Sched& S, const Epi& E, const int K) {
;     ...
;             G_WAIT_V(8); G_WAIT_L(0); G_BAR; G_MMA(1, 0, At, B0); G_MMA(1, 1, At, B1); G_BAR; G_SCHED;
;             G_LDB(B0, 1, 0); G_LDB(B1, 1, 1); G_SCHED; G_LDA(At, 1, 0); G_STAGE_A(G_SA(0, 1), x2, x3, k2);
;             G_WAIT_V(8); G_WAIT_L(0); G_BAR; G_MMA(0, 0, At, B0); G_MMA(0, 1, At, B1); G_BAR; G_SCHED;
	s_setprio 1
	v_mfma_f32_16x16x32_bf16 v[60:63], v[138:141], v[194:197], v[60:63]
	v_mfma_f32_16x16x32_bf16 v[56:59], v[158:161], v[194:197], v[56:59]
	v_mfma_f32_16x16x32_bf16 v[52:55], v[138:141], v[202:205], v[52:55]
	v_mfma_f32_16x16x32_bf16 v[48:51], v[158:161], v[202:205], v[48:51]
	v_mfma_f32_16x16x32_bf16 v[44:47], v[138:141], v[210:213], v[44:47]
	v_mfma_f32_16x16x32_bf16 v[40:43], v[158:161], v[210:213], v[40:43]
	v_mfma_f32_16x16x32_bf16 v[36:39], v[138:141], v[218:221], v[36:39]
	v_mfma_f32_16x16x32_bf16 v[32:35], v[158:161], v[218:221], v[32:35]
	v_mfma_f32_16x16x32_bf16 v[60:63], v[154:157], v[198:201], v[60:63]
	v_mfma_f32_16x16x32_bf16 v[56:59], v[162:165], v[198:201], v[56:59]
	v_mfma_f32_16x16x32_bf16 v[52:55], v[154:157], v[206:209], v[52:55]
	v_mfma_f32_16x16x32_bf16 v[48:51], v[162:165], v[206:209], v[48:51]
	v_mfma_f32_16x16x32_bf16 v[44:47], v[154:157], v[214:217], v[44:47]
	v_mfma_f32_16x16x32_bf16 v[40:43], v[162:165], v[214:217], v[40:43]
	v_mfma_f32_16x16x32_bf16 v[36:39], v[154:157], v[222:225], v[36:39]
	v_mfma_f32_16x16x32_bf16 v[32:35], v[162:165], v[222:225], v[32:35]
	v_mfma_f32_16x16x32_bf16 v[28:31], v[166:169], v[194:197], v[28:31]
	v_mfma_f32_16x16x32_bf16 v[24:27], v[174:177], v[194:197], v[24:27]
	v_mfma_f32_16x16x32_bf16 v[20:23], v[166:169], v[202:205], v[20:23]
	v_mfma_f32_16x16x32_bf16 v[16:19], v[174:177], v[202:205], v[16:19]
	v_mfma_f32_16x16x32_bf16 v[12:15], v[166:169], v[210:213], v[12:15]
	v_mfma_f32_16x16x32_bf16 v[8:11], v[174:177], v[210:213], v[8:11]
	v_mfma_f32_16x16x32_bf16 v[4:7], v[166:169], v[218:221], v[4:7]
	v_mfma_f32_16x16x32_bf16 v[0:3], v[174:177], v[218:221], v[0:3]
	v_mfma_f32_16x16x32_bf16 v[28:31], v[170:173], v[198:201], v[28:31]
	v_mfma_f32_16x16x32_bf16 v[24:27], v[178:181], v[198:201], v[24:27]
	v_mfma_f32_16x16x32_bf16 v[20:23], v[170:173], v[206:209], v[20:23]
	v_mfma_f32_16x16x32_bf16 v[16:19], v[178:181], v[206:209], v[16:19]
	v_mfma_f32_16x16x32_bf16 v[12:15], v[170:173], v[214:217], v[12:15]
	v_mfma_f32_16x16x32_bf16 v[8:11], v[178:181], v[214:217], v[8:11]
	v_mfma_f32_16x16x32_bf16 v[4:7], v[170:173], v[222:225], v[4:7]
	v_mfma_f32_16x16x32_bf16 v[0:3], v[178:181], v[222:225], v[0:3]
	s_setprio 0
	s_barrier
	s_add_i32 s72, 0, 0x18000
	v_add_u32_e32 v142, s72, v148
	s_add_i32 s78, 0, 0x1c000
	ds_read_b128 v[138:141], v142
	ds_read_b128 v[154:157], v142 offset:1024
	ds_read_b128 v[158:161], v142 offset:2048
	ds_read_b128 v[162:165], v142 offset:3072
	v_add_u32_e32 v142, s78, v148
	ds_read_b128 v[166:169], v142
	ds_read_b128 v[170:173], v142 offset:1024
	ds_read_b128 v[174:177], v142 offset:2048
	ds_read_b128 v[178:181], v142 offset:3072
	s_add_i32 s75, s75, s48
	s_mov_b32 m0, s55
	v_add_u32_e32 v142, s75, v133
	s_add_i32 s73, s73, s48
	ds_read_b128 v[194:197], v152 offset:32768
	ds_read_b128 v[198:201], v152 offset:33792
	ds_read_b128 v[202:205], v152 offset:34816
	ds_read_b128 v[206:209], v152 offset:35840
	ds_read_b128 v[210:213], v152 offset:36864
	ds_read_b128 v[214:217], v152 offset:37888
	ds_read_b128 v[218:221], v152 offset:38912
	ds_read_b128 v[222:225], v152 offset:39936
	global_load_lds_dwordx4 v142, s[82:83]
	v_add_u32_e32 v142, s73, v145
	s_mov_b32 m0, s56
	s_nop 0
	global_load_lds_dwordx4 v142, s[82:83]
	s_add_i32 s37, s36, s37
	s_add_i32 s48, s72, s47
	v_add_u32_e32 v142, s37, v144
	s_mov_b32 m0, s48
	s_waitcnt vmcnt(8) lgkmcnt(0)
	s_barrier
; #define G_STAGE_A(bufoff, p0, p1, koff) do { \
;         __builtin_amdgcn_global_load_lds((const unsigned*)(gbase + (size_t)(unsigned)((p0) + (koff) + voffA[0])), (LAS unsigned*)(lds + (bufoff) + ldsw), 16, 0, 0); \
;         __builtin_amdgcn_global_load_lds((const unsigned*)(gbase + (size_t)(unsigned)((p1) + (koff) + voffA[1])), (LAS unsigned*)(lds + (bufoff) + ldsw + 8192), 16, 0, 0); } while (0)
; #define G_STAGE_B(bufoff, p, koff) do { \
;         __builtin_amdgcn_global_load_lds((const unsigned*)(gbase + (size_t)(unsigned)((p) + (koff) + voffB[0])), (LAS unsigned*)(lds + (bufoff) + ldsw), 16, 0, 0); \
;         __builtin_amdgcn_global_load_lds((const unsigned*)(gbase + (size_t)(unsigned)((p) + (koff) + voffB[1])), (LAS unsigned*)(lds + (bufoff) + ldsw + 8192), 16, 0, 0); } while (0)
; #define G_LDA(dst, b, h) do { _Pragma("unroll") for (int m = 0; m < 4; ++m) _Pragma("unroll") for (int k = 0; k < 2; ++k) dst[m][k] = *(const LAS bf16x8*)(lds + G_SA(b, h) + aoff + m * 2048 + k * 1024); } while (0)
; #define G_MMA(ai, bj, At, Bt) do { __builtin_amdgcn_s_setprio(1); _Pragma("unroll") for (int m = 0; m < 4; ++m) _Pragma("unroll") for (int n = 0; n < 2; ++n) _Pragma("unroll") for (int k = 0; k < 2; ++k) \
;         acc[ai][bj][m][n] = __builtin_amdgcn_mfma_f32_16x16x32_bf16(Bt[n][k], At[m][k], acc[ai][bj][m][n], 0, 0, 0); __builtin_amdgcn_s_setprio(0); } while (0)
; #define G_WAIT_V(n) asm volatile("s_waitcnt vmcnt(" #n ")" ::: "memory")
; #define G_WAIT_L(n) asm volatile("s_waitcnt lgkmcnt(" #n ")" ::: "memory")
; #define G_BAR __builtin_amdgcn_s_barrier()
; #define G_SCHED __builtin_amdgcn_sched_barrier(0)
; template <class Epi>
; DI void gemm_phase(LAS unsigned char* lds, const Sched& S, const Epi& E, const int K) {
;     ...
;             G_WAIT_V(8); G_WAIT_L(0); G_BAR; G_MMA(0, 0, At, B0); G_MMA(0, 1, At, B1); G_BAR; G_SCHED;
;             G_LDA(At, 1, 1); G_STAGE_B(G_SB(1, 0), xb, kb3); G_STAGE_B(G_SB(1, 1), xb + hstepB, kb3); G_STAGE_A(G_SA(1, 0), x0, x1, k3);
;             G_WAIT_V(8); G_WAIT_L(0); G_BAR; G_MMA(1, 0, At, B0); G_MMA(1, 1, At, B1); G_BAR; G_SCHED;
;     ...
;         if (wr == 0) G_BAR;
	s_setprio 1
	v_mfma_f32_16x16x32_bf16 v[124:127], v[138:141], v[194:197], v[124:127]
	v_mfma_f32_16x16x32_bf16 v[120:123], v[158:161], v[194:197], v[120:123]
	v_mfma_f32_16x16x32_bf16 v[116:119], v[138:141], v[202:205], v[116:119]
	v_mfma_f32_16x16x32_bf16 v[112:115], v[158:161], v[202:205], v[112:115]
	v_mfma_f32_16x16x32_bf16 v[108:111], v[138:141], v[210:213], v[108:111]
	v_mfma_f32_16x16x32_bf16 v[104:107], v[158:161], v[210:213], v[104:107]
	v_mfma_f32_16x16x32_bf16 v[100:103], v[138:141], v[218:221], v[100:103]
	v_mfma_f32_16x16x32_bf16 v[96:99], v[158:161], v[218:221], v[96:99]
	v_mfma_f32_16x16x32_bf16 v[124:127], v[154:157], v[198:201], v[124:127]
	v_mfma_f32_16x16x32_bf16 v[120:123], v[162:165], v[198:201], v[120:123]
	v_mfma_f32_16x16x32_bf16 v[116:119], v[154:157], v[206:209], v[116:119]
	v_mfma_f32_16x16x32_bf16 v[112:115], v[162:165], v[206:209], v[112:115]
	v_mfma_f32_16x16x32_bf16 v[108:111], v[154:157], v[214:217], v[108:111]
	v_mfma_f32_16x16x32_bf16 v[104:107], v[162:165], v[214:217], v[104:107]
	v_mfma_f32_16x16x32_bf16 v[100:103], v[154:157], v[222:225], v[100:103]
	v_mfma_f32_16x16x32_bf16 v[96:99], v[162:165], v[222:225], v[96:99]
	v_mfma_f32_16x16x32_bf16 v[92:95], v[166:169], v[194:197], v[92:95]
	v_mfma_f32_16x16x32_bf16 v[88:91], v[174:177], v[194:197], v[88:91]
	v_mfma_f32_16x16x32_bf16 v[84:87], v[166:169], v[202:205], v[84:87]
	v_mfma_f32_16x16x32_bf16 v[80:83], v[174:177], v[202:205], v[80:83]
	v_mfma_f32_16x16x32_bf16 v[76:79], v[166:169], v[210:213], v[76:79]
	v_mfma_f32_16x16x32_bf16 v[72:75], v[174:177], v[210:213], v[72:75]
	v_mfma_f32_16x16x32_bf16 v[68:71], v[166:169], v[218:221], v[68:71]
	v_mfma_f32_16x16x32_bf16 v[64:67], v[174:177], v[218:221], v[64:67]
	v_mfma_f32_16x16x32_bf16 v[92:95], v[170:173], v[198:201], v[92:95]
	v_mfma_f32_16x16x32_bf16 v[88:91], v[178:181], v[198:201], v[88:91]
	v_mfma_f32_16x16x32_bf16 v[84:87], v[170:173], v[206:209], v[84:87]
	v_mfma_f32_16x16x32_bf16 v[80:83], v[178:181], v[206:209], v[80:83]
	v_mfma_f32_16x16x32_bf16 v[76:79], v[170:173], v[214:217], v[76:79]
	v_mfma_f32_16x16x32_bf16 v[72:75], v[178:181], v[214:217], v[72:75]
	v_mfma_f32_16x16x32_bf16 v[68:71], v[170:173], v[222:225], v[68:71]
	v_mfma_f32_16x16x32_bf16 v[64:67], v[178:181], v[222:225], v[64:67]
	s_setprio 0
	s_barrier
	ds_read_b128 v[194:197], v152 offset:49152
	ds_read_b128 v[198:201], v152 offset:50176
	ds_read_b128 v[202:205], v152 offset:51200
	ds_read_b128 v[206:209], v152 offset:52224
	ds_read_b128 v[210:213], v152 offset:53248
	ds_read_b128 v[214:217], v152 offset:54272
	ds_read_b128 v[218:221], v152 offset:55296
	ds_read_b128 v[222:225], v152 offset:56320
	global_load_lds_dwordx4 v142, s[82:83]
	v_add_u32_e32 v142, s37, v146
	s_add_i32 m0, s48, 0x2000
	s_add_i32 s26, s36, s26
	s_add_i32 s37, s78, s47
	global_load_lds_dwordx4 v142, s[82:83]
	v_add_u32_e32 v142, s26, v144
	s_mov_b32 m0, s37
	v_add_u32_e32 v130, s36, v130
	global_load_lds_dwordx4 v142, s[82:83]
	v_add_u32_e32 v142, s26, v146
	s_add_i32 m0, s37, 0x2000
	s_nop 0
	global_load_lds_dwordx4 v142, s[82:83]
	s_mov_b32 m0, s57
	s_nop 0
	global_load_lds_dwordx4 v130, s[82:83]
	v_add_u32_e32 v130, s36, v131
	s_mov_b32 m0, s58
	s_nop 0
	global_load_lds_dwordx4 v130, s[82:83]
	s_waitcnt vmcnt(8) lgkmcnt(0)
	s_barrier
	s_setprio 1
	v_mfma_f32_16x16x32_bf16 v[60:63], v[138:141], v[194:197], v[60:63]
	v_mfma_f32_16x16x32_bf16 v[56:59], v[158:161], v[194:197], v[56:59]
	v_mfma_f32_16x16x32_bf16 v[52:55], v[138:141], v[202:205], v[52:55]
	v_mfma_f32_16x16x32_bf16 v[48:51], v[158:161], v[202:205], v[48:51]
	v_mfma_f32_16x16x32_bf16 v[44:47], v[138:141], v[210:213], v[44:47]
	v_mfma_f32_16x16x32_bf16 v[40:43], v[158:161], v[210:213], v[40:43]
	v_mfma_f32_16x16x32_bf16 v[36:39], v[138:141], v[218:221], v[36:39]
	v_mfma_f32_16x16x32_bf16 v[32:35], v[158:161], v[218:221], v[32:35]
	v_mfma_f32_16x16x32_bf16 v[60:63], v[154:157], v[198:201], v[60:63]
	v_mfma_f32_16x16x32_bf16 v[56:59], v[162:165], v[198:201], v[56:59]
	v_mfma_f32_16x16x32_bf16 v[52:55], v[154:157], v[206:209], v[52:55]
	v_mfma_f32_16x16x32_bf16 v[48:51], v[162:165], v[206:209], v[48:51]
	v_mfma_f32_16x16x32_bf16 v[44:47], v[154:157], v[214:217], v[44:47]
	v_mfma_f32_16x16x32_bf16 v[40:43], v[162:165], v[214:217], v[40:43]
	v_mfma_f32_16x16x32_bf16 v[36:39], v[154:157], v[222:225], v[36:39]
	v_mfma_f32_16x16x32_bf16 v[32:35], v[162:165], v[222:225], v[32:35]
	v_mfma_f32_16x16x32_bf16 v[28:31], v[166:169], v[194:197], v[28:31]
	v_mfma_f32_16x16x32_bf16 v[24:27], v[174:177], v[194:197], v[24:27]
	v_mfma_f32_16x16x32_bf16 v[20:23], v[166:169], v[202:205], v[20:23]
	v_mfma_f32_16x16x32_bf16 v[16:19], v[174:177], v[202:205], v[16:19]
	v_mfma_f32_16x16x32_bf16 v[12:15], v[166:169], v[210:213], v[12:15]
	v_mfma_f32_16x16x32_bf16 v[8:11], v[174:177], v[210:213], v[8:11]
	v_mfma_f32_16x16x32_bf16 v[4:7], v[166:169], v[218:221], v[4:7]
	v_mfma_f32_16x16x32_bf16 v[0:3], v[174:177], v[218:221], v[0:3]
	v_mfma_f32_16x16x32_bf16 v[28:31], v[170:173], v[198:201], v[28:31]
	v_mfma_f32_16x16x32_bf16 v[24:27], v[178:181], v[198:201], v[24:27]
	v_mfma_f32_16x16x32_bf16 v[20:23], v[170:173], v[206:209], v[20:23]
	v_mfma_f32_16x16x32_bf16 v[16:19], v[178:181], v[206:209], v[16:19]
	v_mfma_f32_16x16x32_bf16 v[12:15], v[170:173], v[214:217], v[12:15]
	v_mfma_f32_16x16x32_bf16 v[8:11], v[178:181], v[214:217], v[8:11]
	v_mfma_f32_16x16x32_bf16 v[4:7], v[170:173], v[222:225], v[4:7]
	v_mfma_f32_16x16x32_bf16 v[0:3], v[178:181], v[222:225], v[0:3]
	s_setprio 0
	s_barrier
	s_add_i32 s10, s10, 2
	s_cmp_gt_u32 s10, 29
	s_mov_b32 s26, s27
	s_cbranch_scc0 .LBB0_511
	s_and_b64 vcc, exec, s[14:15]
	s_cbranch_vccz .LBB0_514
	s_barrier
